# GEMM steady K-loops: tile-end barrier hoisted before last 2 MFMA groups, next tile's first LDS fragment reads issued under them (cross-tile software pipelining)
# speedup vs baseline: 1.0173x; 1.0053x over previous
; DEVI f32x4 mfma16(bf16x8 a, bf16x8 b, f32x4 c) { return __builtin_amdgcn_mfma_f32_16x16x32_bf16(a, b, c, 0, 0, 0); }
; template <int MODE, class Epi>
; DEVI void gemm256_phase(int sw, const bf16_t* __restrict__ W, int ldw, const bf16_t* __restrict__ X, int ldx, int K, int nN, char* shm, const Epi& epi) {
;     ...
;     for (int t = 0; t < ntk; ++t) {
;       const int cur = (b0 + t) & 1;
;       const bool st_own = t + 1 < ntk, st_next = !st_own && has_next;
;       if (wid < 4) {
;         if (st_own) stage(cur ^ 1, n0, m0, kt0 + t + 1);
;         else if (st_next) stage(cur ^ 1, n1, m1, kt1);
;       }
;       const char* SAp = shm + cur * STAGE_B + wr * (16 * 1024) + lds_lo;
;       const char* SBp = shm + cur * STAGE_B + TILE_B + wc * (8 * 1024) + lds_lo;
; #pragma unroll
;       for (int ks = 0; ks < 2; ++ks) {
;         const int kx = (wid >> 2) ? (1 - 2 * ks) * 1024 : 0;
;         bf16x8 At[8], Bf[4];
; #pragma unroll
;         for (int m = 0; m < 8; ++m) At[m] = *(const bf16x8*)(SAp + (2 * m + ks) * 1024 + kx);
; #pragma unroll
;         for (int n = 0; n < 4; ++n) Bf[n] = *(const bf16x8*)(SBp + (2 * n + ks) * 1024 + kx);
; #pragma unroll
;         for (int m = 0; m < 8; ++m)
; #pragma unroll
;           for (int n = 0; n < 4; ++n) acc[m][n] = mfma16(At[m], Bf[n], acc[m][n]);
;         __builtin_amdgcn_sched_barrier(0);
;         if (ks == 0 && wid >= 4) {
;           if (st_own) stage(cur ^ 1, n0, m0, kt0 + t + 1);
;           else if (st_next) stage(cur ^ 1, n1, m1, kt1);
;         }
;       }
;       asm volatile("s_waitcnt vmcnt(0)" ::: "memory");
;       __syncthreads();
;     }
.LBB0_167:
	v_add_u32_e32 v150, s54, v129
	ds_read_b128 v[220:223], v150 offset:1024
	v_add_u32_e32 v128, s54, v128
	ds_read_b128 v[134:137], v128 offset:33792
	ds_read_b128 v[138:141], v128 offset:35840
	ds_read_b128 v[142:145], v128 offset:37888
	ds_read_b128 v[146:149], v128 offset:39936
	ds_read_b128 v[224:227], v150 offset:3072
	ds_read_b128 v[228:231], v150 offset:5120
	ds_read_b128 v[232:235], v150 offset:7168
	s_waitcnt lgkmcnt(3)
	v_mfma_f32_16x16x32_bf16 v[124:127], v[220:223], v[134:137], v[124:127]
	v_mfma_f32_16x16x32_bf16 v[120:123], v[220:223], v[138:141], v[120:123]
	v_mfma_f32_16x16x32_bf16 v[116:119], v[220:223], v[142:145], v[116:119]
	v_mfma_f32_16x16x32_bf16 v[112:115], v[220:223], v[146:149], v[112:115]
	ds_read_b128 v[236:239], v150 offset:9216
	s_waitcnt lgkmcnt(3)
	v_mfma_f32_16x16x32_bf16 v[108:111], v[224:227], v[134:137], v[108:111]
	v_mfma_f32_16x16x32_bf16 v[104:107], v[224:227], v[138:141], v[104:107]
	v_mfma_f32_16x16x32_bf16 v[100:103], v[224:227], v[142:145], v[100:103]
	v_mfma_f32_16x16x32_bf16 v[96:99], v[224:227], v[146:149], v[96:99]
	ds_read_b128 v[240:243], v150 offset:11264
	s_waitcnt lgkmcnt(3)
	v_mfma_f32_16x16x32_bf16 v[92:95], v[228:231], v[134:137], v[92:95]
	v_mfma_f32_16x16x32_bf16 v[88:91], v[228:231], v[138:141], v[88:91]
	v_mfma_f32_16x16x32_bf16 v[84:87], v[228:231], v[142:145], v[84:87]
	v_mfma_f32_16x16x32_bf16 v[80:83], v[228:231], v[146:149], v[80:83]
	ds_read_b128 v[244:247], v150 offset:13312
	s_waitcnt lgkmcnt(3)
	v_mfma_f32_16x16x32_bf16 v[76:79], v[232:235], v[134:137], v[76:79]
	v_mfma_f32_16x16x32_bf16 v[72:75], v[232:235], v[138:141], v[72:75]
	v_mfma_f32_16x16x32_bf16 v[68:71], v[232:235], v[142:145], v[68:71]
	v_mfma_f32_16x16x32_bf16 v[64:67], v[232:235], v[146:149], v[64:67]
	ds_read_b128 v[248:251], v150 offset:15360
	s_waitcnt lgkmcnt(3)
	v_mfma_f32_16x16x32_bf16 v[60:63], v[236:239], v[134:137], v[60:63]
	v_mfma_f32_16x16x32_bf16 v[56:59], v[236:239], v[138:141], v[56:59]
	v_mfma_f32_16x16x32_bf16 v[52:55], v[236:239], v[142:145], v[52:55]
	v_mfma_f32_16x16x32_bf16 v[48:51], v[236:239], v[146:149], v[48:51]
	s_waitcnt lgkmcnt(2)
	v_mfma_f32_16x16x32_bf16 v[44:47], v[240:243], v[134:137], v[44:47]
	v_mfma_f32_16x16x32_bf16 v[40:43], v[240:243], v[138:141], v[40:43]
	v_mfma_f32_16x16x32_bf16 v[36:39], v[240:243], v[142:145], v[36:39]
	v_mfma_f32_16x16x32_bf16 v[32:35], v[240:243], v[146:149], v[32:35]
	s_addk_i32 s67, 0x80
	s_cmp_eq_u32 s66, s68
	s_cbranch_scc1 .Lmy_xexit_168
	s_add_i32 s0, s45, s68
	s_and_b32 s69, s0, 1
	s_add_i32 s68, s68, 1
	s_cmp_lt_i32 s68, s46
	s_cselect_b64 s[0:1], -1, 0
	s_cmp_ge_i32 s68, s46
	s_cselect_b64 s[8:9], -1, 0
	v_cndmask_b32_e64 v128, 0, 1, s[0:1]
	s_and_b64 s[8:9], s[2:3], s[8:9]
	s_andn2_b64 vcc, exec, s[36:37]
	v_cmp_ne_u32_e64 s[0:1], 1, v128
	s_lshl_b32 s10, s69, 16
	s_add_i32 s11, s10, s47
	v_add_u32_e32 v129, s11, v194
	v_add_u32_e32 v253, s53, v129
	s_or_b32 s11, s10, s52
	v_add_u32_e32 v128, s11, v194
	v_add_u32_e32 v252, s53, v128
	s_waitcnt lgkmcnt(0)
	s_waitcnt vmcnt(0)
	s_barrier
	ds_read_b128 v[220:223], v253
	v_mfma_f32_16x16x32_bf16 v[28:31], v[244:247], v[134:137], v[28:31]
	v_mfma_f32_16x16x32_bf16 v[12:15], v[248:251], v[134:137], v[12:15]
	ds_read_b128 v[134:137], v252 offset:32768
	v_mfma_f32_16x16x32_bf16 v[24:27], v[244:247], v[138:141], v[24:27]
	v_mfma_f32_16x16x32_bf16 v[8:11], v[248:251], v[138:141], v[8:11]
	ds_read_b128 v[138:141], v252 offset:34816
	v_mfma_f32_16x16x32_bf16 v[20:23], v[244:247], v[142:145], v[20:23]
	v_mfma_f32_16x16x32_bf16 v[4:7], v[248:251], v[142:145], v[4:7]
	ds_read_b128 v[142:145], v252 offset:36864
	v_mfma_f32_16x16x32_bf16 v[16:19], v[244:247], v[146:149], v[16:19]
	v_mfma_f32_16x16x32_bf16 v[0:3], v[248:251], v[146:149], v[0:3]
	ds_read_b128 v[146:149], v252 offset:38912
	ds_read_b128 v[224:227], v253 offset:2048
	ds_read_b128 v[228:231], v253 offset:4096
	ds_read_b128 v[232:235], v253 offset:6144
	v_mov_b32_e32 v150, v253
	s_branch .Lmy_xf_168
.Lmy_xexit_168:
	s_waitcnt lgkmcnt(1)
	v_mfma_f32_16x16x32_bf16 v[28:31], v[244:247], v[134:137], v[28:31]
	v_mfma_f32_16x16x32_bf16 v[24:27], v[244:247], v[138:141], v[24:27]
	v_mfma_f32_16x16x32_bf16 v[20:23], v[244:247], v[142:145], v[20:23]
	v_mfma_f32_16x16x32_bf16 v[16:19], v[244:247], v[146:149], v[16:19]
	s_waitcnt lgkmcnt(0)
	v_mfma_f32_16x16x32_bf16 v[12:15], v[248:251], v[134:137], v[12:15]
	v_mfma_f32_16x16x32_bf16 v[8:11], v[248:251], v[138:141], v[8:11]
	v_mfma_f32_16x16x32_bf16 v[4:7], v[248:251], v[142:145], v[4:7]
	v_mfma_f32_16x16x32_bf16 v[0:3], v[248:251], v[146:149], v[0:3]
	s_waitcnt vmcnt(0)
	s_barrier
	s_branch .LBB0_186

; DEVI f32x4 mfma16(bf16x8 a, bf16x8 b, f32x4 c) { return __builtin_amdgcn_mfma_f32_16x16x32_bf16(a, b, c, 0, 0, 0); }
; template <int MODE, class Epi>
; DEVI void gemm256_phase(int sw, const bf16_t* __restrict__ W, int ldw, const bf16_t* __restrict__ X, int ldx, int K, int nN, char* shm, const Epi& epi) {
;     ...
;   auto stage = [&](int buf, int n0, int m0, int kt) {
;     const char* wk = (const char*)(W + (size_t)n0 * ldw) + kt * 128;
;     const char* xk = (const char*)(X + (size_t)m0 * ldx) + kt * 128;
; #pragma unroll
;     for (int i = 0; i < 4; ++i) {
;       unsigned ow = offW[i], ox = offX[i];
;       asm volatile("" : "+v"(ow), "+v"(ox));
;       __builtin_amdgcn_global_load_lds((const unsigned*)(wk + ow), (unsigned*)(shm + buf * STAGE_B + wid * 1024 + i * 8192), 16, 0, 0);
;       __builtin_amdgcn_global_load_lds((const unsigned*)(xk + ox), (unsigned*)(shm + buf * STAGE_B + TILE_B + wid * 1024 + i * 8192), 16, 0, 0);
;     }
;     ...
;       for (int ks = 0; ks < 2; ++ks) {
;         const int kx = (wid >> 2) ? (1 - 2 * ks) * 1024 : 0;
;         bf16x8 At[8], Bf[4];
; #pragma unroll
;         for (int m = 0; m < 8; ++m) At[m] = *(const bf16x8*)(SAp + (2 * m + ks) * 1024 + kx);
; #pragma unroll
;         for (int n = 0; n < 4; ++n) Bf[n] = *(const bf16x8*)(SBp + (2 * n + ks) * 1024 + kx);
; #pragma unroll
;         for (int m = 0; m < 8; ++m)
; #pragma unroll
;           for (int n = 0; n < 4; ++n) acc[m][n] = mfma16(At[m], Bf[n], acc[m][n]);
;         __builtin_amdgcn_sched_barrier(0);
;         if (ks == 0 && wid >= 4) {
;           if (st_own) stage(cur ^ 1, n0, m0, kt0 + t + 1);
;           else if (st_next) stage(cur ^ 1, n1, m1, kt1);
;         }
.Lmy_xf_168:
	s_add_u32 s98, s62, s67
	s_addc_u32 s99, s63, 0
	s_add_u32 s98, s98, 0x80
	s_addc_u32 s99, s99, 0
	s_add_u32 s100, s64, s67
	s_addc_u32 s101, s65, 0
	s_add_u32 s100, s100, 0x80
	s_addc_u32 s101, s101, 0
	s_xor_b32 m0, s10, 0x10000
	s_add_i32 m0, m0, s44
	s_waitcnt lgkmcnt(3)
	v_mfma_f32_16x16x32_bf16 v[124:127], v[220:223], v[134:137], v[124:127]
	v_mfma_f32_16x16x32_bf16 v[120:123], v[220:223], v[138:141], v[120:123]
	v_mfma_f32_16x16x32_bf16 v[116:119], v[220:223], v[142:145], v[116:119]
	v_mfma_f32_16x16x32_bf16 v[112:115], v[220:223], v[146:149], v[112:115]
	global_load_lds_dwordx4 v190, s[98:99]
	ds_read_b128 v[236:239], v150 offset:8192
	s_add_i32 m0, m0, 0x8000
	s_waitcnt lgkmcnt(3)
	v_mfma_f32_16x16x32_bf16 v[108:111], v[224:227], v[134:137], v[108:111]
	v_mfma_f32_16x16x32_bf16 v[104:107], v[224:227], v[138:141], v[104:107]
	v_mfma_f32_16x16x32_bf16 v[100:103], v[224:227], v[142:145], v[100:103]
	v_mfma_f32_16x16x32_bf16 v[96:99], v[224:227], v[146:149], v[96:99]
	global_load_lds_dwordx4 v190, s[100:101]
	ds_read_b128 v[240:243], v150 offset:10240
	s_add_i32 m0, m0, 0xffffa000
	s_waitcnt lgkmcnt(3)
	v_mfma_f32_16x16x32_bf16 v[92:95], v[228:231], v[134:137], v[92:95]
	v_mfma_f32_16x16x32_bf16 v[88:91], v[228:231], v[138:141], v[88:91]
	v_mfma_f32_16x16x32_bf16 v[84:87], v[228:231], v[142:145], v[84:87]
	v_mfma_f32_16x16x32_bf16 v[80:83], v[228:231], v[146:149], v[80:83]
	global_load_lds_dwordx4 v191, s[98:99]
	ds_read_b128 v[244:247], v150 offset:12288
	s_add_i32 m0, m0, 0x8000
	s_waitcnt lgkmcnt(3)
	v_mfma_f32_16x16x32_bf16 v[76:79], v[232:235], v[134:137], v[76:79]
	v_mfma_f32_16x16x32_bf16 v[72:75], v[232:235], v[138:141], v[72:75]
	v_mfma_f32_16x16x32_bf16 v[68:71], v[232:235], v[142:145], v[68:71]
	v_mfma_f32_16x16x32_bf16 v[64:67], v[232:235], v[146:149], v[64:67]
	global_load_lds_dwordx4 v191, s[100:101]
	ds_read_b128 v[248:251], v150 offset:14336
	s_add_i32 m0, m0, 0xffffa000
	s_waitcnt lgkmcnt(3)
	v_mfma_f32_16x16x32_bf16 v[60:63], v[236:239], v[134:137], v[60:63]
	v_mfma_f32_16x16x32_bf16 v[56:59], v[236:239], v[138:141], v[56:59]
	v_mfma_f32_16x16x32_bf16 v[52:55], v[236:239], v[142:145], v[52:55]
	v_mfma_f32_16x16x32_bf16 v[48:51], v[236:239], v[146:149], v[48:51]
	global_load_lds_dwordx4 v192, s[98:99]
	s_add_i32 m0, m0, 0x8000
	s_waitcnt lgkmcnt(2)
	v_mfma_f32_16x16x32_bf16 v[44:47], v[240:243], v[134:137], v[44:47]
	v_mfma_f32_16x16x32_bf16 v[40:43], v[240:243], v[138:141], v[40:43]
	v_mfma_f32_16x16x32_bf16 v[36:39], v[240:243], v[142:145], v[36:39]
	v_mfma_f32_16x16x32_bf16 v[32:35], v[240:243], v[146:149], v[32:35]
	global_load_lds_dwordx4 v192, s[100:101]
	s_add_i32 m0, m0, 0xffffa000
	s_waitcnt lgkmcnt(1)
	v_mfma_f32_16x16x32_bf16 v[28:31], v[244:247], v[134:137], v[28:31]
	v_mfma_f32_16x16x32_bf16 v[24:27], v[244:247], v[138:141], v[24:27]
	v_mfma_f32_16x16x32_bf16 v[20:23], v[244:247], v[142:145], v[20:23]
	v_mfma_f32_16x16x32_bf16 v[16:19], v[244:247], v[146:149], v[16:19]
	global_load_lds_dwordx4 v193, s[98:99]
	s_add_i32 m0, m0, 0x8000
	s_waitcnt lgkmcnt(0)
	v_mfma_f32_16x16x32_bf16 v[12:15], v[248:251], v[134:137], v[12:15]
	v_mfma_f32_16x16x32_bf16 v[8:11], v[248:251], v[138:141], v[8:11]
	v_mfma_f32_16x16x32_bf16 v[4:7], v[248:251], v[142:145], v[4:7]
	v_mfma_f32_16x16x32_bf16 v[0:3], v[248:251], v[146:149], v[0:3]
	global_load_lds_dwordx4 v193, s[100:101]
	s_andn2_b64 vcc, exec, s[30:31]
	s_branch .LBB0_167
	s_and_b64 vcc, exec, s[0:1]
	s_xor_b32 s42, s10, 0x10000
	s_cbranch_vccnz .LBB0_180
	s_ashr_i32 s10, s67, 31
	s_add_u32 s12, s62, s67
	s_addc_u32 s13, s63, s10
	s_add_u32 s0, s12, 0x80
	s_addc_u32 s1, s13, 0
	s_add_u32 s14, s64, s67
	s_addc_u32 s15, s65, s10
	s_add_u32 s10, s14, 0x80
	v_mov_b32_e32 v130, v190
	v_mov_b32_e32 v188, v190
	s_addc_u32 s11, s15, 0
	s_add_i32 s43, s44, s42
	v_lshl_add_u64 v[132:133], s[12:13], 0, v[188:189]
	v_mov_b32_e32 v131, v189
	v_lshl_add_u64 v[132:133], v[132:133], 0, s[38:39]
	s_mov_b32 m0, s43
	v_lshl_add_u64 v[130:131], s[14:15], 0, v[130:131]
	global_load_lds_dwordx4 v[132:133], off
	v_lshl_add_u64 v[130:131], v[130:131], 0, s[38:39]
	s_add_i32 m0, s43, 0x8000
	v_mov_b32_e32 v188, v191
	global_load_lds_dwordx4 v[130:131], off
	v_mov_b32_e32 v130, v191
	v_mov_b32_e32 v131, v189
	v_lshl_add_u64 v[132:133], s[12:13], 0, v[188:189]
	v_lshl_add_u64 v[132:133], v[132:133], 0, s[38:39]
	s_add_i32 m0, s43, 0x2000
	v_lshl_add_u64 v[130:131], s[14:15], 0, v[130:131]
	global_load_lds_dwordx4 v[132:133], off
	v_lshl_add_u64 v[130:131], v[130:131], 0, s[38:39]
	s_add_i32 m0, s43, 0xa000
	v_mov_b32_e32 v188, v192
	global_load_lds_dwordx4 v[130:131], off
	v_mov_b32_e32 v130, v192
	v_mov_b32_e32 v131, v189
	v_lshl_add_u64 v[132:133], s[12:13], 0, v[188:189]
	v_lshl_add_u64 v[132:133], v[132:133], 0, s[38:39]
	s_add_i32 m0, s43, 0x4000
	v_lshl_add_u64 v[130:131], s[14:15], 0, v[130:131]
	global_load_lds_dwordx4 v[132:133], off
	v_lshl_add_u64 v[130:131], v[130:131], 0, s[38:39]
	s_add_i32 m0, s43, 0xc000
	s_nop 0
	global_load_lds_dwordx4 v[130:131], off
	v_mov_b32_e32 v130, v193
	v_mov_b32_e32 v131, v193
	s_mov_b64 s[12:13], -1
	s_cbranch_execz .LBB0_181
	s_branch .LBB0_184

; DEVI f32x4 mfma16(bf16x8 a, bf16x8 b, f32x4 c) { return __builtin_amdgcn_mfma_f32_16x16x32_bf16(a, b, c, 0, 0, 0); }
; template <int MODE, class Epi>
; DEVI void gemm256_phase(int sw, const bf16_t* __restrict__ W, int ldw, const bf16_t* __restrict__ X, int ldx, int K, int nN, char* shm, const Epi& epi) {
;     ...
;     for (int t = 0; t < ntk; ++t) {
;       const int cur = (b0 + t) & 1;
;       const bool st_own = t + 1 < ntk, st_next = !st_own && has_next;
;       if (wid < 4) {
;         if (st_own) stage(cur ^ 1, n0, m0, kt0 + t + 1);
;         else if (st_next) stage(cur ^ 1, n1, m1, kt1);
;       }
;       const char* SAp = shm + cur * STAGE_B + wr * (16 * 1024) + lds_lo;
;       const char* SBp = shm + cur * STAGE_B + TILE_B + wc * (8 * 1024) + lds_lo;
; #pragma unroll
;       for (int ks = 0; ks < 2; ++ks) {
;         const int kx = (wid >> 2) ? (1 - 2 * ks) * 1024 : 0;
;         bf16x8 At[8], Bf[4];
; #pragma unroll
;         for (int m = 0; m < 8; ++m) At[m] = *(const bf16x8*)(SAp + (2 * m + ks) * 1024 + kx);
; #pragma unroll
;         for (int n = 0; n < 4; ++n) Bf[n] = *(const bf16x8*)(SBp + (2 * n + ks) * 1024 + kx);
; #pragma unroll
;         for (int m = 0; m < 8; ++m)
; #pragma unroll
;           for (int n = 0; n < 4; ++n) acc[m][n] = mfma16(At[m], Bf[n], acc[m][n]);
;         __builtin_amdgcn_sched_barrier(0);
;         if (ks == 0 && wid >= 4) {
;           if (st_own) stage(cur ^ 1, n0, m0, kt0 + t + 1);
;           else if (st_next) stage(cur ^ 1, n1, m1, kt1);
;         }
;       }
;       asm volatile("s_waitcnt vmcnt(0)" ::: "memory");
;       __syncthreads();
;     }
.LBB0_703:
	v_add_u32_e32 v154, s63, v129
	ds_read_b128 v[220:223], v154 offset:1024
	v_add_u32_e32 v128, s63, v128
	ds_read_b128 v[134:137], v128 offset:33792
	ds_read_b128 v[224:227], v154 offset:3072
	ds_read_b128 v[142:145], v128 offset:35840
	ds_read_b128 v[146:149], v128 offset:37888
	ds_read_b128 v[150:153], v128 offset:39936
	ds_read_b128 v[228:231], v154 offset:5120
	ds_read_b128 v[232:235], v154 offset:7168
	s_waitcnt lgkmcnt(2)
	v_mfma_f32_16x16x32_bf16 v[124:127], v[220:223], v[134:137], v[124:127]
	v_mfma_f32_16x16x32_bf16 v[120:123], v[220:223], v[142:145], v[120:123]
	v_mfma_f32_16x16x32_bf16 v[116:119], v[220:223], v[146:149], v[116:119]
	v_mfma_f32_16x16x32_bf16 v[112:115], v[220:223], v[150:153], v[112:115]
	ds_read_b128 v[236:239], v154 offset:9216
	s_waitcnt lgkmcnt(3)
	v_mfma_f32_16x16x32_bf16 v[108:111], v[224:227], v[134:137], v[108:111]
	v_mfma_f32_16x16x32_bf16 v[104:107], v[224:227], v[142:145], v[104:107]
	v_mfma_f32_16x16x32_bf16 v[100:103], v[224:227], v[146:149], v[100:103]
	v_mfma_f32_16x16x32_bf16 v[96:99], v[224:227], v[150:153], v[96:99]
	ds_read_b128 v[240:243], v154 offset:11264
	s_waitcnt lgkmcnt(3)
	v_mfma_f32_16x16x32_bf16 v[92:95], v[228:231], v[134:137], v[92:95]
	v_mfma_f32_16x16x32_bf16 v[88:91], v[228:231], v[142:145], v[88:91]
	v_mfma_f32_16x16x32_bf16 v[84:87], v[228:231], v[146:149], v[84:87]
	v_mfma_f32_16x16x32_bf16 v[80:83], v[228:231], v[150:153], v[80:83]
	ds_read_b128 v[244:247], v154 offset:13312
	s_waitcnt lgkmcnt(3)
	v_mfma_f32_16x16x32_bf16 v[76:79], v[232:235], v[134:137], v[76:79]
	v_mfma_f32_16x16x32_bf16 v[72:75], v[232:235], v[142:145], v[72:75]
	v_mfma_f32_16x16x32_bf16 v[68:71], v[232:235], v[146:149], v[68:71]
	v_mfma_f32_16x16x32_bf16 v[64:67], v[232:235], v[150:153], v[64:67]
	ds_read_b128 v[248:251], v154 offset:15360
	s_waitcnt lgkmcnt(3)
	v_mfma_f32_16x16x32_bf16 v[60:63], v[236:239], v[134:137], v[60:63]
	v_mfma_f32_16x16x32_bf16 v[56:59], v[236:239], v[142:145], v[56:59]
	v_mfma_f32_16x16x32_bf16 v[52:55], v[236:239], v[146:149], v[52:55]
	v_mfma_f32_16x16x32_bf16 v[48:51], v[236:239], v[150:153], v[48:51]
	s_waitcnt lgkmcnt(2)
	v_mfma_f32_16x16x32_bf16 v[44:47], v[240:243], v[134:137], v[44:47]
	v_mfma_f32_16x16x32_bf16 v[40:43], v[240:243], v[142:145], v[40:43]
	v_mfma_f32_16x16x32_bf16 v[36:39], v[240:243], v[146:149], v[36:39]
	v_mfma_f32_16x16x32_bf16 v[32:35], v[240:243], v[150:153], v[32:35]
	s_addk_i32 s81, 0x80
	s_cmp_eq_u32 s80, s82
	s_cbranch_scc1 .Lmy_xexit_704
	s_add_i32 s0, s61, s82
	s_and_b32 s83, s0, 1
	s_add_i32 s82, s82, 1
	s_cmp_lt_i32 s82, s54
	s_cselect_b64 s[0:1], -1, 0
	s_cmp_ge_i32 s82, s54
	s_cselect_b64 s[40:41], -1, 0
	v_cmp_ne_u32_e32 vcc, 1, v197
	v_cndmask_b32_e64 v128, 0, 1, s[0:1]
	s_and_b64 s[40:41], s[38:39], s[40:41]
	v_cmp_ne_u32_e64 s[0:1], 1, v128
	s_lshl_b32 s42, s83, 16
	s_add_i32 s43, s42, s58
	v_add_u32_e32 v129, s43, v194
	v_add_u32_e32 v253, s62, v129
	s_or_b32 s43, s42, s59
	v_add_u32_e32 v128, s43, v194
	v_add_u32_e32 v252, s62, v128
	s_waitcnt lgkmcnt(0)
	s_waitcnt vmcnt(0)
	s_barrier
	ds_read_b128 v[220:223], v253
	ds_read_b128 v[138:141], v252 offset:34816
	v_mfma_f32_16x16x32_bf16 v[28:31], v[244:247], v[134:137], v[28:31]
	v_mfma_f32_16x16x32_bf16 v[12:15], v[248:251], v[134:137], v[12:15]
	ds_read_b128 v[134:137], v252 offset:32768
	v_mfma_f32_16x16x32_bf16 v[24:27], v[244:247], v[142:145], v[24:27]
	v_mfma_f32_16x16x32_bf16 v[8:11], v[248:251], v[142:145], v[8:11]
	ds_read_b128 v[142:145], v252 offset:36864
	v_mfma_f32_16x16x32_bf16 v[20:23], v[244:247], v[146:149], v[20:23]
	v_mfma_f32_16x16x32_bf16 v[4:7], v[248:251], v[146:149], v[4:7]
	ds_read_b128 v[146:149], v252 offset:38912
	v_mfma_f32_16x16x32_bf16 v[16:19], v[244:247], v[150:153], v[16:19]
	v_mfma_f32_16x16x32_bf16 v[0:3], v[248:251], v[150:153], v[0:3]
	ds_read_b128 v[224:227], v253 offset:2048
	ds_read_b128 v[228:231], v253 offset:4096
	ds_read_b128 v[232:235], v253 offset:6144
	v_mov_b32_e32 v150, v253
	s_branch .Lmy_xf_704
.Lmy_xexit_704:
	s_waitcnt lgkmcnt(1)
	v_mfma_f32_16x16x32_bf16 v[28:31], v[244:247], v[134:137], v[28:31]
	v_mfma_f32_16x16x32_bf16 v[24:27], v[244:247], v[142:145], v[24:27]
	v_mfma_f32_16x16x32_bf16 v[20:23], v[244:247], v[146:149], v[20:23]
	v_mfma_f32_16x16x32_bf16 v[16:19], v[244:247], v[150:153], v[16:19]
	s_waitcnt lgkmcnt(0)
	v_mfma_f32_16x16x32_bf16 v[12:15], v[248:251], v[134:137], v[12:15]
	v_mfma_f32_16x16x32_bf16 v[8:11], v[248:251], v[142:145], v[8:11]
	v_mfma_f32_16x16x32_bf16 v[4:7], v[248:251], v[146:149], v[4:7]
	v_mfma_f32_16x16x32_bf16 v[0:3], v[248:251], v[150:153], v[0:3]
	s_waitcnt vmcnt(0)
	s_barrier
	s_branch .LBB0_724

; DEVI f32x4 mfma16(bf16x8 a, bf16x8 b, f32x4 c) { return __builtin_amdgcn_mfma_f32_16x16x32_bf16(a, b, c, 0, 0, 0); }
; template <int MODE, class Epi>
; DEVI void gemm256_phase(int sw, const bf16_t* __restrict__ W, int ldw, const bf16_t* __restrict__ X, int ldx, int K, int nN, char* shm, const Epi& epi) {
;     ...
;   auto stage = [&](int buf, int n0, int m0, int kt) {
;     const char* wk = (const char*)(W + (size_t)n0 * ldw) + kt * 128;
;     const char* xk = (const char*)(X + (size_t)m0 * ldx) + kt * 128;
; #pragma unroll
;     for (int i = 0; i < 4; ++i) {
;       unsigned ow = offW[i], ox = offX[i];
;       asm volatile("" : "+v"(ow), "+v"(ox));
;       __builtin_amdgcn_global_load_lds((const unsigned*)(wk + ow), (unsigned*)(shm + buf * STAGE_B + wid * 1024 + i * 8192), 16, 0, 0);
;       __builtin_amdgcn_global_load_lds((const unsigned*)(xk + ox), (unsigned*)(shm + buf * STAGE_B + TILE_B + wid * 1024 + i * 8192), 16, 0, 0);
;     }
;     ...
;       for (int ks = 0; ks < 2; ++ks) {
;         const int kx = (wid >> 2) ? (1 - 2 * ks) * 1024 : 0;
;         bf16x8 At[8], Bf[4];
; #pragma unroll
;         for (int m = 0; m < 8; ++m) At[m] = *(const bf16x8*)(SAp + (2 * m + ks) * 1024 + kx);
; #pragma unroll
;         for (int n = 0; n < 4; ++n) Bf[n] = *(const bf16x8*)(SBp + (2 * n + ks) * 1024 + kx);
; #pragma unroll
;         for (int m = 0; m < 8; ++m)
; #pragma unroll
;           for (int n = 0; n < 4; ++n) acc[m][n] = mfma16(At[m], Bf[n], acc[m][n]);
;         __builtin_amdgcn_sched_barrier(0);
;         if (ks == 0 && wid >= 4) {
;           if (st_own) stage(cur ^ 1, n0, m0, kt0 + t + 1);
;           else if (st_next) stage(cur ^ 1, n1, m1, kt1);
;         }
.Lmy_xf_704:
	s_add_u32 s98, s78, s81
	s_addc_u32 s99, s79, 0
	s_add_u32 s98, s98, 0x80
	s_addc_u32 s99, s99, 0
	s_add_u32 s100, s76, s81
	s_addc_u32 s101, s77, 0
	s_add_u32 s100, s100, 0x80
	s_addc_u32 s101, s101, 0
	s_xor_b32 m0, s42, 0x10000
	s_add_i32 m0, m0, s57
	s_waitcnt lgkmcnt(3)
	v_mfma_f32_16x16x32_bf16 v[124:127], v[220:223], v[134:137], v[124:127]
	v_mfma_f32_16x16x32_bf16 v[120:123], v[220:223], v[138:141], v[120:123]
	v_mfma_f32_16x16x32_bf16 v[116:119], v[220:223], v[142:145], v[116:119]
	v_mfma_f32_16x16x32_bf16 v[112:115], v[220:223], v[146:149], v[112:115]
	global_load_lds_dwordx4 v190, s[98:99]
	ds_read_b128 v[236:239], v150 offset:8192
	s_add_i32 m0, m0, 0x8000
	s_waitcnt lgkmcnt(3)
	v_mfma_f32_16x16x32_bf16 v[108:111], v[224:227], v[134:137], v[108:111]
	v_mfma_f32_16x16x32_bf16 v[104:107], v[224:227], v[138:141], v[104:107]
	v_mfma_f32_16x16x32_bf16 v[100:103], v[224:227], v[142:145], v[100:103]
	v_mfma_f32_16x16x32_bf16 v[96:99], v[224:227], v[146:149], v[96:99]
	global_load_lds_dwordx4 v190, s[100:101]
	ds_read_b128 v[240:243], v150 offset:10240
	s_add_i32 m0, m0, 0xffffa000
	s_waitcnt lgkmcnt(3)
	v_mfma_f32_16x16x32_bf16 v[92:95], v[228:231], v[134:137], v[92:95]
	v_mfma_f32_16x16x32_bf16 v[88:91], v[228:231], v[138:141], v[88:91]
	v_mfma_f32_16x16x32_bf16 v[84:87], v[228:231], v[142:145], v[84:87]
	v_mfma_f32_16x16x32_bf16 v[80:83], v[228:231], v[146:149], v[80:83]
	global_load_lds_dwordx4 v191, s[98:99]
	ds_read_b128 v[244:247], v150 offset:12288
	s_add_i32 m0, m0, 0x8000
	s_waitcnt lgkmcnt(3)
	v_mfma_f32_16x16x32_bf16 v[76:79], v[232:235], v[134:137], v[76:79]
	v_mfma_f32_16x16x32_bf16 v[72:75], v[232:235], v[138:141], v[72:75]
	v_mfma_f32_16x16x32_bf16 v[68:71], v[232:235], v[142:145], v[68:71]
	v_mfma_f32_16x16x32_bf16 v[64:67], v[232:235], v[146:149], v[64:67]
	global_load_lds_dwordx4 v191, s[100:101]
	ds_read_b128 v[248:251], v150 offset:14336
	s_add_i32 m0, m0, 0xffffa000
	s_waitcnt lgkmcnt(3)
	v_mfma_f32_16x16x32_bf16 v[60:63], v[236:239], v[134:137], v[60:63]
	v_mfma_f32_16x16x32_bf16 v[56:59], v[236:239], v[138:141], v[56:59]
	v_mfma_f32_16x16x32_bf16 v[52:55], v[236:239], v[142:145], v[52:55]
	v_mfma_f32_16x16x32_bf16 v[48:51], v[236:239], v[146:149], v[48:51]
	global_load_lds_dwordx4 v192, s[98:99]
	s_add_i32 m0, m0, 0x8000
	s_waitcnt lgkmcnt(2)
	v_mfma_f32_16x16x32_bf16 v[44:47], v[240:243], v[134:137], v[44:47]
	v_mfma_f32_16x16x32_bf16 v[40:43], v[240:243], v[138:141], v[40:43]
	v_mfma_f32_16x16x32_bf16 v[36:39], v[240:243], v[142:145], v[36:39]
	v_mfma_f32_16x16x32_bf16 v[32:35], v[240:243], v[146:149], v[32:35]
	global_load_lds_dwordx4 v192, s[100:101]
	s_add_i32 m0, m0, 0xffffa000
	s_waitcnt lgkmcnt(1)
	v_mfma_f32_16x16x32_bf16 v[28:31], v[244:247], v[134:137], v[28:31]
	v_mfma_f32_16x16x32_bf16 v[24:27], v[244:247], v[138:141], v[24:27]
	v_mfma_f32_16x16x32_bf16 v[20:23], v[244:247], v[142:145], v[20:23]
	v_mfma_f32_16x16x32_bf16 v[16:19], v[244:247], v[146:149], v[16:19]
	global_load_lds_dwordx4 v193, s[98:99]
	s_add_i32 m0, m0, 0x8000
	s_waitcnt lgkmcnt(0)
	v_mfma_f32_16x16x32_bf16 v[12:15], v[248:251], v[134:137], v[12:15]
	v_mfma_f32_16x16x32_bf16 v[8:11], v[248:251], v[138:141], v[8:11]
	v_mfma_f32_16x16x32_bf16 v[4:7], v[248:251], v[142:145], v[4:7]
	v_mfma_f32_16x16x32_bf16 v[0:3], v[248:251], v[146:149], v[0:3]
	global_load_lds_dwordx4 v193, s[100:101]
	s_andn2_b64 vcc, exec, s[8:9]
	s_branch .LBB0_703
	s_and_b64 vcc, exec, s[0:1]
	s_xor_b32 s52, s42, 0x10000
	s_cbranch_vccnz .LBB0_716
	s_ashr_i32 s42, s81, 31
	s_add_u32 s44, s78, s81
	s_addc_u32 s45, s79, s42
	s_add_u32 s0, s44, 0x80
	s_addc_u32 s1, s45, 0
	s_add_u32 s46, s76, s81
	s_addc_u32 s47, s77, s42
	s_add_u32 s42, s46, 0x80
	v_mov_b32_e32 v188, v190
	v_mov_b32_e32 v130, v190
	s_addc_u32 s43, s47, 0
	s_add_i32 s53, s57, s52
	v_lshl_add_u64 v[132:133], s[44:45], 0, v[188:189]
	v_mov_b32_e32 v131, v189
	v_lshl_add_u64 v[132:133], v[132:133], 0, s[10:11]
	s_mov_b32 m0, s53
	v_lshl_add_u64 v[130:131], s[46:47], 0, v[130:131]
	global_load_lds_dwordx4 v[132:133], off
	v_lshl_add_u64 v[130:131], v[130:131], 0, s[10:11]
	s_add_i32 m0, s53, 0x8000
	v_mov_b32_e32 v188, v191
	global_load_lds_dwordx4 v[130:131], off
	v_mov_b32_e32 v130, v191
	v_mov_b32_e32 v131, v189
	v_lshl_add_u64 v[132:133], s[44:45], 0, v[188:189]
	v_lshl_add_u64 v[132:133], v[132:133], 0, s[10:11]
	s_add_i32 m0, s53, 0x2000
	v_lshl_add_u64 v[130:131], s[46:47], 0, v[130:131]
	global_load_lds_dwordx4 v[132:133], off
	v_lshl_add_u64 v[130:131], v[130:131], 0, s[10:11]
	s_add_i32 m0, s53, 0xa000
	v_mov_b32_e32 v188, v192
	global_load_lds_dwordx4 v[130:131], off
	v_mov_b32_e32 v130, v192
	v_mov_b32_e32 v131, v189
	v_lshl_add_u64 v[132:133], s[44:45], 0, v[188:189]
	v_lshl_add_u64 v[132:133], v[132:133], 0, s[10:11]
	s_add_i32 m0, s53, 0x4000
	v_lshl_add_u64 v[130:131], s[46:47], 0, v[130:131]
	global_load_lds_dwordx4 v[132:133], off
	v_lshl_add_u64 v[130:131], v[130:131], 0, s[10:11]
	s_add_i32 m0, s53, 0xc000
	s_nop 0
	global_load_lds_dwordx4 v[130:131], off
	v_mov_b32_e32 v130, v193
	v_mov_b32_e32 v131, v193
	s_mov_b64 s[44:45], -1
	s_cbranch_execz .LBB0_717
	s_branch .LBB0_720

; DEVI f32x4 mfma16(bf16x8 a, bf16x8 b, f32x4 c) { return __builtin_amdgcn_mfma_f32_16x16x32_bf16(a, b, c, 0, 0, 0); }
; template <int MODE, class Epi>
; DEVI void gemm256_phase(int sw, const bf16_t* __restrict__ W, int ldw, const bf16_t* __restrict__ X, int ldx, int K, int nN, char* shm, const Epi& epi) {
;     ...
;     for (int t = 0; t < ntk; ++t) {
;       const int cur = (b0 + t) & 1;
;       const bool st_own = t + 1 < ntk, st_next = !st_own && has_next;
;       if (wid < 4) {
;         if (st_own) stage(cur ^ 1, n0, m0, kt0 + t + 1);
;         else if (st_next) stage(cur ^ 1, n1, m1, kt1);
;       }
;       const char* SAp = shm + cur * STAGE_B + wr * (16 * 1024) + lds_lo;
;       const char* SBp = shm + cur * STAGE_B + TILE_B + wc * (8 * 1024) + lds_lo;
; #pragma unroll
;       for (int ks = 0; ks < 2; ++ks) {
;         const int kx = (wid >> 2) ? (1 - 2 * ks) * 1024 : 0;
;         bf16x8 At[8], Bf[4];
; #pragma unroll
;         for (int m = 0; m < 8; ++m) At[m] = *(const bf16x8*)(SAp + (2 * m + ks) * 1024 + kx);
; #pragma unroll
;         for (int n = 0; n < 4; ++n) Bf[n] = *(const bf16x8*)(SBp + (2 * n + ks) * 1024 + kx);
; #pragma unroll
;         for (int m = 0; m < 8; ++m)
; #pragma unroll
;           for (int n = 0; n < 4; ++n) acc[m][n] = mfma16(At[m], Bf[n], acc[m][n]);
;         __builtin_amdgcn_sched_barrier(0);
;         if (ks == 0 && wid >= 4) {
;           if (st_own) stage(cur ^ 1, n0, m0, kt0 + t + 1);
;           else if (st_next) stage(cur ^ 1, n1, m1, kt1);
;         }
;       }
;       asm volatile("s_waitcnt vmcnt(0)" ::: "memory");
;       __syncthreads();
;     }
.LBB0_984:
	v_add_u32_e32 v154, s42, v129
	ds_read_b128 v[220:223], v154 offset:1024
	v_add_u32_e32 v128, s42, v128
	ds_read_b128 v[134:137], v128 offset:33792
	ds_read_b128 v[224:227], v154 offset:3072
	ds_read_b128 v[142:145], v128 offset:35840
	ds_read_b128 v[146:149], v128 offset:37888
	ds_read_b128 v[150:153], v128 offset:39936
	s_add_i32 s58, s58, 1
	ds_read_b128 v[228:231], v154 offset:5120
	ds_read_b128 v[232:235], v154 offset:7168
	s_waitcnt lgkmcnt(2)
	v_mfma_f32_16x16x32_bf16 v[124:127], v[220:223], v[134:137], v[124:127]
	v_mfma_f32_16x16x32_bf16 v[120:123], v[220:223], v[142:145], v[120:123]
	v_mfma_f32_16x16x32_bf16 v[116:119], v[220:223], v[146:149], v[116:119]
	v_mfma_f32_16x16x32_bf16 v[112:115], v[220:223], v[150:153], v[112:115]
	ds_read_b128 v[236:239], v154 offset:9216
	s_waitcnt lgkmcnt(3)
	v_mfma_f32_16x16x32_bf16 v[108:111], v[224:227], v[134:137], v[108:111]
	v_mfma_f32_16x16x32_bf16 v[104:107], v[224:227], v[142:145], v[104:107]
	v_mfma_f32_16x16x32_bf16 v[100:103], v[224:227], v[146:149], v[100:103]
	v_mfma_f32_16x16x32_bf16 v[96:99], v[224:227], v[150:153], v[96:99]
	ds_read_b128 v[240:243], v154 offset:11264
	s_waitcnt lgkmcnt(3)
	v_mfma_f32_16x16x32_bf16 v[92:95], v[228:231], v[134:137], v[92:95]
	v_mfma_f32_16x16x32_bf16 v[88:91], v[228:231], v[142:145], v[88:91]
	v_mfma_f32_16x16x32_bf16 v[84:87], v[228:231], v[146:149], v[84:87]
	v_mfma_f32_16x16x32_bf16 v[80:83], v[228:231], v[150:153], v[80:83]
	ds_read_b128 v[244:247], v154 offset:13312
	s_waitcnt lgkmcnt(3)
	v_mfma_f32_16x16x32_bf16 v[76:79], v[232:235], v[134:137], v[76:79]
	v_mfma_f32_16x16x32_bf16 v[72:75], v[232:235], v[142:145], v[72:75]
	v_mfma_f32_16x16x32_bf16 v[68:71], v[232:235], v[146:149], v[68:71]
	v_mfma_f32_16x16x32_bf16 v[64:67], v[232:235], v[150:153], v[64:67]
	ds_read_b128 v[248:251], v154 offset:15360
	s_waitcnt lgkmcnt(3)
	v_mfma_f32_16x16x32_bf16 v[60:63], v[236:239], v[134:137], v[60:63]
	v_mfma_f32_16x16x32_bf16 v[56:59], v[236:239], v[142:145], v[56:59]
	v_mfma_f32_16x16x32_bf16 v[52:55], v[236:239], v[146:149], v[52:55]
	v_mfma_f32_16x16x32_bf16 v[48:51], v[236:239], v[150:153], v[48:51]
	s_waitcnt lgkmcnt(2)
	v_mfma_f32_16x16x32_bf16 v[44:47], v[240:243], v[134:137], v[44:47]
	v_mfma_f32_16x16x32_bf16 v[40:43], v[240:243], v[142:145], v[40:43]
	v_mfma_f32_16x16x32_bf16 v[36:39], v[240:243], v[146:149], v[36:39]
	v_mfma_f32_16x16x32_bf16 v[32:35], v[240:243], v[150:153], v[32:35]
	s_addk_i32 s57, 0x80
	s_cmp_eq_u32 s54, s58
	s_cbranch_scc1 .Lmy_xexit_985
	s_add_i32 s10, s37, s58
	s_and_b32 s60, s10, 1
	s_mov_b64 s[10:11], -1
	s_and_b64 vcc, exec, s[4:5]
	s_lshl_b32 s59, s60, 16
	s_add_i32 s10, s59, s38
	v_add_u32_e32 v129, s10, v198
	v_add_u32_e32 v253, s41, v129
	s_add_i32 s10, s59, s39
	v_add_u32_e32 v128, s10, v198
	v_add_u32_e32 v252, s41, v128
	s_waitcnt lgkmcnt(0)
	s_waitcnt vmcnt(0)
	s_barrier
	ds_read_b128 v[220:223], v253
	ds_read_b128 v[224:227], v253 offset:2048
	v_mfma_f32_16x16x32_bf16 v[28:31], v[244:247], v[134:137], v[28:31]
	v_mfma_f32_16x16x32_bf16 v[12:15], v[248:251], v[134:137], v[12:15]
	ds_read_b128 v[134:137], v252 offset:32768
	v_mfma_f32_16x16x32_bf16 v[24:27], v[244:247], v[142:145], v[24:27]
	v_mfma_f32_16x16x32_bf16 v[8:11], v[248:251], v[142:145], v[8:11]
	ds_read_b128 v[142:145], v252 offset:34816
	v_mfma_f32_16x16x32_bf16 v[20:23], v[244:247], v[146:149], v[20:23]
	v_mfma_f32_16x16x32_bf16 v[4:7], v[248:251], v[146:149], v[4:7]
	ds_read_b128 v[146:149], v252 offset:36864
	v_mfma_f32_16x16x32_bf16 v[16:19], v[244:247], v[150:153], v[16:19]
	v_mfma_f32_16x16x32_bf16 v[0:3], v[248:251], v[150:153], v[0:3]
	ds_read_b128 v[150:153], v252 offset:38912
	ds_read_b128 v[228:231], v253 offset:4096
	ds_read_b128 v[232:235], v253 offset:6144
	v_mov_b32_e32 v154, v253
	s_branch .Lmy_xf_985

; DEVI f32x4 mfma16(bf16x8 a, bf16x8 b, f32x4 c) { return __builtin_amdgcn_mfma_f32_16x16x32_bf16(a, b, c, 0, 0, 0); }
; template <int MODE, class Epi>
; DEVI void gemm256_phase(int sw, const bf16_t* __restrict__ W, int ldw, const bf16_t* __restrict__ X, int ldx, int K, int nN, char* shm, const Epi& epi) {
;     ...
;   auto stage = [&](int buf, int n0, int m0, int kt) {
;     const char* wk = (const char*)(W + (size_t)n0 * ldw) + kt * 128;
;     const char* xk = (const char*)(X + (size_t)m0 * ldx) + kt * 128;
; #pragma unroll
;     for (int i = 0; i < 4; ++i) {
;       unsigned ow = offW[i], ox = offX[i];
;       asm volatile("" : "+v"(ow), "+v"(ox));
;       __builtin_amdgcn_global_load_lds((const unsigned*)(wk + ow), (unsigned*)(shm + buf * STAGE_B + wid * 1024 + i * 8192), 16, 0, 0);
;       __builtin_amdgcn_global_load_lds((const unsigned*)(xk + ox), (unsigned*)(shm + buf * STAGE_B + TILE_B + wid * 1024 + i * 8192), 16, 0, 0);
;     }
;     ...
;       for (int ks = 0; ks < 2; ++ks) {
;         const int kx = (wid >> 2) ? (1 - 2 * ks) * 1024 : 0;
;         bf16x8 At[8], Bf[4];
; #pragma unroll
;         for (int m = 0; m < 8; ++m) At[m] = *(const bf16x8*)(SAp + (2 * m + ks) * 1024 + kx);
; #pragma unroll
;         for (int n = 0; n < 4; ++n) Bf[n] = *(const bf16x8*)(SBp + (2 * n + ks) * 1024 + kx);
; #pragma unroll
;         for (int m = 0; m < 8; ++m)
; #pragma unroll
;           for (int n = 0; n < 4; ++n) acc[m][n] = mfma16(At[m], Bf[n], acc[m][n]);
;         __builtin_amdgcn_sched_barrier(0);
;         if (ks == 0 && wid >= 4) {
;           if (st_own) stage(cur ^ 1, n0, m0, kt0 + t + 1);
;           else if (st_next) stage(cur ^ 1, n1, m1, kt1);
;         }
.Lmy_xf_985:
	s_add_u32 s98, s12, s57
	s_addc_u32 s99, s13, 0
	s_add_u32 s98, s98, 0x80
	s_addc_u32 s99, s99, 0
	s_add_u32 s100, s55, s57
	s_addc_u32 s101, s56, 0
	s_add_u32 s100, s100, 0x80
	s_addc_u32 s101, s101, 0
	s_xor_b32 m0, s59, 0x10000
	s_add_i32 m0, m0, s14
	s_waitcnt lgkmcnt(2)
	v_mfma_f32_16x16x32_bf16 v[124:127], v[220:223], v[134:137], v[124:127]
	v_mfma_f32_16x16x32_bf16 v[120:123], v[220:223], v[142:145], v[120:123]
	v_mfma_f32_16x16x32_bf16 v[116:119], v[220:223], v[146:149], v[116:119]
	v_mfma_f32_16x16x32_bf16 v[112:115], v[220:223], v[150:153], v[112:115]
	global_load_lds_dwordx4 v194, s[98:99]
	ds_read_b128 v[236:239], v154 offset:8192
	s_add_i32 m0, m0, 0x8000
	s_waitcnt lgkmcnt(3)
	v_mfma_f32_16x16x32_bf16 v[108:111], v[224:227], v[134:137], v[108:111]
	v_mfma_f32_16x16x32_bf16 v[104:107], v[224:227], v[142:145], v[104:107]
	v_mfma_f32_16x16x32_bf16 v[100:103], v[224:227], v[146:149], v[100:103]
	v_mfma_f32_16x16x32_bf16 v[96:99], v[224:227], v[150:153], v[96:99]
	global_load_lds_dwordx4 v194, s[100:101]
	ds_read_b128 v[240:243], v154 offset:10240
	s_add_i32 m0, m0, 0xffffa000
	s_waitcnt lgkmcnt(3)
	v_mfma_f32_16x16x32_bf16 v[92:95], v[228:231], v[134:137], v[92:95]
	v_mfma_f32_16x16x32_bf16 v[88:91], v[228:231], v[142:145], v[88:91]
	v_mfma_f32_16x16x32_bf16 v[84:87], v[228:231], v[146:149], v[84:87]
	v_mfma_f32_16x16x32_bf16 v[80:83], v[228:231], v[150:153], v[80:83]
	global_load_lds_dwordx4 v195, s[98:99]
	ds_read_b128 v[244:247], v154 offset:12288
	s_add_i32 m0, m0, 0x8000
	s_waitcnt lgkmcnt(3)
	v_mfma_f32_16x16x32_bf16 v[76:79], v[232:235], v[134:137], v[76:79]
	v_mfma_f32_16x16x32_bf16 v[72:75], v[232:235], v[142:145], v[72:75]
	v_mfma_f32_16x16x32_bf16 v[68:71], v[232:235], v[146:149], v[68:71]
	v_mfma_f32_16x16x32_bf16 v[64:67], v[232:235], v[150:153], v[64:67]
	global_load_lds_dwordx4 v195, s[100:101]
	ds_read_b128 v[248:251], v154 offset:14336
	s_add_i32 m0, m0, 0xffffa000
	s_waitcnt lgkmcnt(3)
	v_mfma_f32_16x16x32_bf16 v[60:63], v[236:239], v[134:137], v[60:63]
	v_mfma_f32_16x16x32_bf16 v[56:59], v[236:239], v[142:145], v[56:59]
	v_mfma_f32_16x16x32_bf16 v[52:55], v[236:239], v[146:149], v[52:55]
	v_mfma_f32_16x16x32_bf16 v[48:51], v[236:239], v[150:153], v[48:51]
	global_load_lds_dwordx4 v196, s[98:99]
	s_add_i32 m0, m0, 0x8000
	s_waitcnt lgkmcnt(2)
	v_mfma_f32_16x16x32_bf16 v[44:47], v[240:243], v[134:137], v[44:47]
	v_mfma_f32_16x16x32_bf16 v[40:43], v[240:243], v[142:145], v[40:43]
	v_mfma_f32_16x16x32_bf16 v[36:39], v[240:243], v[146:149], v[36:39]
	v_mfma_f32_16x16x32_bf16 v[32:35], v[240:243], v[150:153], v[32:35]
	global_load_lds_dwordx4 v196, s[100:101]
	s_add_i32 m0, m0, 0xffffa000
	s_waitcnt lgkmcnt(1)
	v_mfma_f32_16x16x32_bf16 v[28:31], v[244:247], v[134:137], v[28:31]
	v_mfma_f32_16x16x32_bf16 v[24:27], v[244:247], v[142:145], v[24:27]
	v_mfma_f32_16x16x32_bf16 v[20:23], v[244:247], v[146:149], v[20:23]
	v_mfma_f32_16x16x32_bf16 v[16:19], v[244:247], v[150:153], v[16:19]
	global_load_lds_dwordx4 v197, s[98:99]
	s_add_i32 m0, m0, 0x8000
	s_waitcnt lgkmcnt(0)
	v_mfma_f32_16x16x32_bf16 v[12:15], v[248:251], v[134:137], v[12:15]
	v_mfma_f32_16x16x32_bf16 v[8:11], v[248:251], v[142:145], v[8:11]
	v_mfma_f32_16x16x32_bf16 v[4:7], v[248:251], v[146:149], v[4:7]
	v_mfma_f32_16x16x32_bf16 v[0:3], v[248:251], v[150:153], v[0:3]
	global_load_lds_dwordx4 v197, s[100:101]
	s_and_b64 vcc, exec, s[0:1]
	s_branch .LBB0_984
	s_xor_b32 s10, s59, 0x10000
	s_add_i32 s59, s14, s10
	s_add_i32 s62, s59, 0xe000
	s_add_i32 s63, s59, 0x6000
	s_add_i32 s64, s59, 0xc000
	s_add_i32 s65, s59, 0x4000
	s_add_i32 s66, s59, 0xa000
	s_add_i32 s67, s59, 0x2000
	s_add_i32 s68, s59, 0x8000
	s_ashr_i32 s61, s57, 31
	s_add_u32 s10, s55, s57
	s_addc_u32 s11, s56, s61
	s_add_u32 s60, s12, s57
	s_addc_u32 s61, s13, s61
	v_mov_b32_e32 v192, v194
	v_mov_b32_e32 v130, v194
	v_mov_b32_e32 v131, v193
	v_lshl_add_u64 v[132:133], s[60:61], 0, v[192:193]
	v_lshl_add_u64 v[132:133], v[132:133], 0, s[6:7]
	s_mov_b32 m0, s59
	v_lshl_add_u64 v[130:131], s[10:11], 0, v[130:131]
	global_load_lds_dwordx4 v[132:133], off
	v_lshl_add_u64 v[130:131], v[130:131], 0, s[6:7]
	s_mov_b32 m0, s68
	v_mov_b32_e32 v192, v195
	global_load_lds_dwordx4 v[130:131], off
	v_mov_b32_e32 v130, v195
	v_mov_b32_e32 v131, v193
	v_lshl_add_u64 v[132:133], s[60:61], 0, v[192:193]
	v_lshl_add_u64 v[132:133], v[132:133], 0, s[6:7]
	s_mov_b32 m0, s67
	v_lshl_add_u64 v[130:131], s[10:11], 0, v[130:131]
	global_load_lds_dwordx4 v[132:133], off
	v_lshl_add_u64 v[130:131], v[130:131], 0, s[6:7]
	s_mov_b32 m0, s66
	v_mov_b32_e32 v192, v196
	global_load_lds_dwordx4 v[130:131], off
	v_mov_b32_e32 v130, v196
	v_mov_b32_e32 v131, v193
	v_lshl_add_u64 v[132:133], s[60:61], 0, v[192:193]
	v_lshl_add_u64 v[132:133], v[132:133], 0, s[6:7]
	s_mov_b32 m0, s65
	v_lshl_add_u64 v[130:131], s[10:11], 0, v[130:131]
	global_load_lds_dwordx4 v[132:133], off
	v_lshl_add_u64 v[130:131], v[130:131], 0, s[6:7]
	s_mov_b32 m0, s64
	v_mov_b32_e32 v192, v197
	global_load_lds_dwordx4 v[130:131], off
	v_mov_b32_e32 v130, v197
	v_mov_b32_e32 v131, v193
	v_lshl_add_u64 v[132:133], s[60:61], 0, v[192:193]
	v_lshl_add_u64 v[132:133], v[132:133], 0, s[6:7]
	s_mov_b32 m0, s63
	v_lshl_add_u64 v[130:131], s[10:11], 0, v[130:131]
	global_load_lds_dwordx4 v[132:133], off
	v_lshl_add_u64 v[130:131], v[130:131], 0, s[6:7]
	s_mov_b32 m0, s62
	s_nop 0
	global_load_lds_dwordx4 v[130:131], off
	s_branch .LBB0_984

; DEVI f32x4 mfma16(bf16x8 a, bf16x8 b, f32x4 c) { return __builtin_amdgcn_mfma_f32_16x16x32_bf16(a, b, c, 0, 0, 0); }
; template <int MODE, class Epi>
; DEVI void gemm256_phase(int sw, const bf16_t* __restrict__ W, int ldw, const bf16_t* __restrict__ X, int ldx, int K, int nN, char* shm, const Epi& epi) {
;     ...
;     for (int t = 0; t < ntk; ++t) {
;       const int cur = (b0 + t) & 1;
;       const bool st_own = t + 1 < ntk, st_next = !st_own && has_next;
;       if (wid < 4) {
;         if (st_own) stage(cur ^ 1, n0, m0, kt0 + t + 1);
;         else if (st_next) stage(cur ^ 1, n1, m1, kt1);
;       }
;       const char* SAp = shm + cur * STAGE_B + wr * (16 * 1024) + lds_lo;
;       const char* SBp = shm + cur * STAGE_B + TILE_B + wc * (8 * 1024) + lds_lo;
; #pragma unroll
;       for (int ks = 0; ks < 2; ++ks) {
;         const int kx = (wid >> 2) ? (1 - 2 * ks) * 1024 : 0;
;         bf16x8 At[8], Bf[4];
; #pragma unroll
;         for (int m = 0; m < 8; ++m) At[m] = *(const bf16x8*)(SAp + (2 * m + ks) * 1024 + kx);
; #pragma unroll
;         for (int n = 0; n < 4; ++n) Bf[n] = *(const bf16x8*)(SBp + (2 * n + ks) * 1024 + kx);
; #pragma unroll
;         for (int m = 0; m < 8; ++m)
; #pragma unroll
;           for (int n = 0; n < 4; ++n) acc[m][n] = mfma16(At[m], Bf[n], acc[m][n]);
;         __builtin_amdgcn_sched_barrier(0);
;         if (ks == 0 && wid >= 4) {
;           if (st_own) stage(cur ^ 1, n0, m0, kt0 + t + 1);
;           else if (st_next) stage(cur ^ 1, n1, m1, kt1);
;         }
;       }
;       asm volatile("s_waitcnt vmcnt(0)" ::: "memory");
;       __syncthreads();
;     }
.LBB0_1033:
	v_add_u32_e32 v154, s63, v129
	ds_read_b128 v[220:223], v154 offset:1024
	v_add_u32_e32 v128, s63, v128
	ds_read_b128 v[134:137], v128 offset:33792
	ds_read_b128 v[224:227], v154 offset:3072
	ds_read_b128 v[142:145], v128 offset:35840
	ds_read_b128 v[146:149], v128 offset:37888
	ds_read_b128 v[150:153], v128 offset:39936
	ds_read_b128 v[228:231], v154 offset:5120
	ds_read_b128 v[232:235], v154 offset:7168
	s_waitcnt lgkmcnt(2)
	v_mfma_f32_16x16x32_bf16 v[124:127], v[220:223], v[134:137], v[124:127]
	v_mfma_f32_16x16x32_bf16 v[120:123], v[220:223], v[142:145], v[120:123]
	v_mfma_f32_16x16x32_bf16 v[116:119], v[220:223], v[146:149], v[116:119]
	v_mfma_f32_16x16x32_bf16 v[112:115], v[220:223], v[150:153], v[112:115]
	ds_read_b128 v[236:239], v154 offset:9216
	s_waitcnt lgkmcnt(3)
	v_mfma_f32_16x16x32_bf16 v[108:111], v[224:227], v[134:137], v[108:111]
	v_mfma_f32_16x16x32_bf16 v[104:107], v[224:227], v[142:145], v[104:107]
	v_mfma_f32_16x16x32_bf16 v[100:103], v[224:227], v[146:149], v[100:103]
	v_mfma_f32_16x16x32_bf16 v[96:99], v[224:227], v[150:153], v[96:99]
	ds_read_b128 v[240:243], v154 offset:11264
	s_waitcnt lgkmcnt(3)
	v_mfma_f32_16x16x32_bf16 v[92:95], v[228:231], v[134:137], v[92:95]
	v_mfma_f32_16x16x32_bf16 v[88:91], v[228:231], v[142:145], v[88:91]
	v_mfma_f32_16x16x32_bf16 v[84:87], v[228:231], v[146:149], v[84:87]
	v_mfma_f32_16x16x32_bf16 v[80:83], v[228:231], v[150:153], v[80:83]
	ds_read_b128 v[244:247], v154 offset:13312
	s_waitcnt lgkmcnt(3)
	v_mfma_f32_16x16x32_bf16 v[76:79], v[232:235], v[134:137], v[76:79]
	v_mfma_f32_16x16x32_bf16 v[72:75], v[232:235], v[142:145], v[72:75]
	v_mfma_f32_16x16x32_bf16 v[68:71], v[232:235], v[146:149], v[68:71]
	v_mfma_f32_16x16x32_bf16 v[64:67], v[232:235], v[150:153], v[64:67]
	ds_read_b128 v[248:251], v154 offset:15360
	s_waitcnt lgkmcnt(3)
	v_mfma_f32_16x16x32_bf16 v[60:63], v[236:239], v[134:137], v[60:63]
	v_mfma_f32_16x16x32_bf16 v[56:59], v[236:239], v[142:145], v[56:59]
	v_mfma_f32_16x16x32_bf16 v[52:55], v[236:239], v[146:149], v[52:55]
	v_mfma_f32_16x16x32_bf16 v[48:51], v[236:239], v[150:153], v[48:51]
	s_waitcnt lgkmcnt(2)
	v_mfma_f32_16x16x32_bf16 v[44:47], v[240:243], v[134:137], v[44:47]
	v_mfma_f32_16x16x32_bf16 v[40:43], v[240:243], v[142:145], v[40:43]
	v_mfma_f32_16x16x32_bf16 v[36:39], v[240:243], v[146:149], v[36:39]
	v_mfma_f32_16x16x32_bf16 v[32:35], v[240:243], v[150:153], v[32:35]
	s_addk_i32 s81, 0x80
	s_cmp_eq_u32 s80, s82
	s_cbranch_scc1 .Lmy_xexit_1034
	s_add_i32 s0, s61, s82
	s_and_b32 s83, s0, 1
	s_add_i32 s82, s82, 1
	s_cmp_lt_i32 s82, s54
	s_cselect_b64 s[0:1], -1, 0
	s_cmp_ge_i32 s82, s54
	s_cselect_b64 s[40:41], -1, 0
	v_cmp_ne_u32_e32 vcc, 1, v197
	v_cndmask_b32_e64 v128, 0, 1, s[0:1]
	s_and_b64 s[40:41], s[38:39], s[40:41]
	v_cmp_ne_u32_e64 s[0:1], 1, v128
	s_lshl_b32 s42, s83, 16
	s_add_i32 s43, s42, s58
	v_add_u32_e32 v129, s43, v194
	v_add_u32_e32 v253, s62, v129
	s_or_b32 s43, s42, s59
	v_add_u32_e32 v128, s43, v194
	v_add_u32_e32 v252, s62, v128
	s_waitcnt lgkmcnt(0)
	s_waitcnt vmcnt(0)
	s_barrier
	ds_read_b128 v[220:223], v253
	ds_read_b128 v[224:227], v253 offset:2048
	v_mfma_f32_16x16x32_bf16 v[28:31], v[244:247], v[134:137], v[28:31]
	v_mfma_f32_16x16x32_bf16 v[12:15], v[248:251], v[134:137], v[12:15]
	ds_read_b128 v[134:137], v252 offset:32768
	v_mfma_f32_16x16x32_bf16 v[24:27], v[244:247], v[142:145], v[24:27]
	v_mfma_f32_16x16x32_bf16 v[8:11], v[248:251], v[142:145], v[8:11]
	ds_read_b128 v[142:145], v252 offset:34816
	v_mfma_f32_16x16x32_bf16 v[20:23], v[244:247], v[146:149], v[20:23]
	v_mfma_f32_16x16x32_bf16 v[4:7], v[248:251], v[146:149], v[4:7]
	ds_read_b128 v[146:149], v252 offset:36864
	v_mfma_f32_16x16x32_bf16 v[16:19], v[244:247], v[150:153], v[16:19]
	v_mfma_f32_16x16x32_bf16 v[0:3], v[248:251], v[150:153], v[0:3]
	ds_read_b128 v[150:153], v252 offset:38912
	ds_read_b128 v[228:231], v253 offset:4096
	ds_read_b128 v[232:235], v253 offset:6144
	v_mov_b32_e32 v154, v253
	s_branch .Lmy_xf_1034

; DEVI f32x4 mfma16(bf16x8 a, bf16x8 b, f32x4 c) { return __builtin_amdgcn_mfma_f32_16x16x32_bf16(a, b, c, 0, 0, 0); }
; template <int MODE, class Epi>
; DEVI void gemm256_phase(int sw, const bf16_t* __restrict__ W, int ldw, const bf16_t* __restrict__ X, int ldx, int K, int nN, char* shm, const Epi& epi) {
;     ...
;   auto stage = [&](int buf, int n0, int m0, int kt) {
;     const char* wk = (const char*)(W + (size_t)n0 * ldw) + kt * 128;
;     const char* xk = (const char*)(X + (size_t)m0 * ldx) + kt * 128;
; #pragma unroll
;     for (int i = 0; i < 4; ++i) {
;       unsigned ow = offW[i], ox = offX[i];
;       asm volatile("" : "+v"(ow), "+v"(ox));
;       __builtin_amdgcn_global_load_lds((const unsigned*)(wk + ow), (unsigned*)(shm + buf * STAGE_B + wid * 1024 + i * 8192), 16, 0, 0);
;       __builtin_amdgcn_global_load_lds((const unsigned*)(xk + ox), (unsigned*)(shm + buf * STAGE_B + TILE_B + wid * 1024 + i * 8192), 16, 0, 0);
;     }
;     ...
;       for (int ks = 0; ks < 2; ++ks) {
;         const int kx = (wid >> 2) ? (1 - 2 * ks) * 1024 : 0;
;         bf16x8 At[8], Bf[4];
; #pragma unroll
;         for (int m = 0; m < 8; ++m) At[m] = *(const bf16x8*)(SAp + (2 * m + ks) * 1024 + kx);
; #pragma unroll
;         for (int n = 0; n < 4; ++n) Bf[n] = *(const bf16x8*)(SBp + (2 * n + ks) * 1024 + kx);
; #pragma unroll
;         for (int m = 0; m < 8; ++m)
; #pragma unroll
;           for (int n = 0; n < 4; ++n) acc[m][n] = mfma16(At[m], Bf[n], acc[m][n]);
;         __builtin_amdgcn_sched_barrier(0);
;         if (ks == 0 && wid >= 4) {
;           if (st_own) stage(cur ^ 1, n0, m0, kt0 + t + 1);
;           else if (st_next) stage(cur ^ 1, n1, m1, kt1);
;         }
.Lmy_xf_1034:
	s_add_u32 s98, s78, s81
	s_addc_u32 s99, s79, 0
	s_add_u32 s98, s98, 0x80
	s_addc_u32 s99, s99, 0
	s_add_u32 s100, s76, s81
	s_addc_u32 s101, s77, 0
	s_add_u32 s100, s100, 0x80
	s_addc_u32 s101, s101, 0
	s_xor_b32 m0, s42, 0x10000
	s_add_i32 m0, m0, s57
	s_waitcnt lgkmcnt(2)
	v_mfma_f32_16x16x32_bf16 v[124:127], v[220:223], v[134:137], v[124:127]
	v_mfma_f32_16x16x32_bf16 v[120:123], v[220:223], v[142:145], v[120:123]
	v_mfma_f32_16x16x32_bf16 v[116:119], v[220:223], v[146:149], v[116:119]
	v_mfma_f32_16x16x32_bf16 v[112:115], v[220:223], v[150:153], v[112:115]
	global_load_lds_dwordx4 v190, s[98:99]
	ds_read_b128 v[236:239], v154 offset:8192
	s_add_i32 m0, m0, 0x8000
	s_waitcnt lgkmcnt(3)
	v_mfma_f32_16x16x32_bf16 v[108:111], v[224:227], v[134:137], v[108:111]
	v_mfma_f32_16x16x32_bf16 v[104:107], v[224:227], v[142:145], v[104:107]
	v_mfma_f32_16x16x32_bf16 v[100:103], v[224:227], v[146:149], v[100:103]
	v_mfma_f32_16x16x32_bf16 v[96:99], v[224:227], v[150:153], v[96:99]
	global_load_lds_dwordx4 v190, s[100:101]
	ds_read_b128 v[240:243], v154 offset:10240
	s_add_i32 m0, m0, 0xffffa000
	s_waitcnt lgkmcnt(3)
	v_mfma_f32_16x16x32_bf16 v[92:95], v[228:231], v[134:137], v[92:95]
	v_mfma_f32_16x16x32_bf16 v[88:91], v[228:231], v[142:145], v[88:91]
	v_mfma_f32_16x16x32_bf16 v[84:87], v[228:231], v[146:149], v[84:87]
	v_mfma_f32_16x16x32_bf16 v[80:83], v[228:231], v[150:153], v[80:83]
	global_load_lds_dwordx4 v191, s[98:99]
	ds_read_b128 v[244:247], v154 offset:12288
	s_add_i32 m0, m0, 0x8000
	s_waitcnt lgkmcnt(3)
	v_mfma_f32_16x16x32_bf16 v[76:79], v[232:235], v[134:137], v[76:79]
	v_mfma_f32_16x16x32_bf16 v[72:75], v[232:235], v[142:145], v[72:75]
	v_mfma_f32_16x16x32_bf16 v[68:71], v[232:235], v[146:149], v[68:71]
	v_mfma_f32_16x16x32_bf16 v[64:67], v[232:235], v[150:153], v[64:67]
	global_load_lds_dwordx4 v191, s[100:101]
	ds_read_b128 v[248:251], v154 offset:14336
	s_add_i32 m0, m0, 0xffffa000
	s_waitcnt lgkmcnt(3)
	v_mfma_f32_16x16x32_bf16 v[60:63], v[236:239], v[134:137], v[60:63]
	v_mfma_f32_16x16x32_bf16 v[56:59], v[236:239], v[142:145], v[56:59]
	v_mfma_f32_16x16x32_bf16 v[52:55], v[236:239], v[146:149], v[52:55]
	v_mfma_f32_16x16x32_bf16 v[48:51], v[236:239], v[150:153], v[48:51]
	global_load_lds_dwordx4 v192, s[98:99]
	s_add_i32 m0, m0, 0x8000
	s_waitcnt lgkmcnt(2)
	v_mfma_f32_16x16x32_bf16 v[44:47], v[240:243], v[134:137], v[44:47]
	v_mfma_f32_16x16x32_bf16 v[40:43], v[240:243], v[142:145], v[40:43]
	v_mfma_f32_16x16x32_bf16 v[36:39], v[240:243], v[146:149], v[36:39]
	v_mfma_f32_16x16x32_bf16 v[32:35], v[240:243], v[150:153], v[32:35]
	global_load_lds_dwordx4 v192, s[100:101]
	s_add_i32 m0, m0, 0xffffa000
	s_waitcnt lgkmcnt(1)
	v_mfma_f32_16x16x32_bf16 v[28:31], v[244:247], v[134:137], v[28:31]
	v_mfma_f32_16x16x32_bf16 v[24:27], v[244:247], v[142:145], v[24:27]
	v_mfma_f32_16x16x32_bf16 v[20:23], v[244:247], v[146:149], v[20:23]
	v_mfma_f32_16x16x32_bf16 v[16:19], v[244:247], v[150:153], v[16:19]
	global_load_lds_dwordx4 v193, s[98:99]
	s_add_i32 m0, m0, 0x8000
	s_waitcnt lgkmcnt(0)
	v_mfma_f32_16x16x32_bf16 v[12:15], v[248:251], v[134:137], v[12:15]
	v_mfma_f32_16x16x32_bf16 v[8:11], v[248:251], v[142:145], v[8:11]
	v_mfma_f32_16x16x32_bf16 v[4:7], v[248:251], v[146:149], v[4:7]
	v_mfma_f32_16x16x32_bf16 v[0:3], v[248:251], v[150:153], v[0:3]
	global_load_lds_dwordx4 v193, s[100:101]
	s_andn2_b64 vcc, exec, s[8:9]
	s_branch .LBB0_1033
	s_and_b64 vcc, exec, s[0:1]
	s_xor_b32 s52, s42, 0x10000
	s_cbranch_vccnz .LBB0_1046
	s_ashr_i32 s42, s81, 31
	s_add_u32 s44, s78, s81
	s_addc_u32 s45, s79, s42
	s_add_u32 s0, s44, 0x80
	s_addc_u32 s1, s45, 0
	s_add_u32 s46, s76, s81
	s_addc_u32 s47, s77, s42
	s_add_u32 s42, s46, 0x80
	v_mov_b32_e32 v188, v190
	v_mov_b32_e32 v130, v190
	s_addc_u32 s43, s47, 0
	s_add_i32 s53, s57, s52
	v_lshl_add_u64 v[132:133], s[44:45], 0, v[188:189]
	v_mov_b32_e32 v131, v189
	v_lshl_add_u64 v[132:133], v[132:133], 0, s[10:11]
	s_mov_b32 m0, s53
	v_lshl_add_u64 v[130:131], s[46:47], 0, v[130:131]
	global_load_lds_dwordx4 v[132:133], off
	v_lshl_add_u64 v[130:131], v[130:131], 0, s[10:11]
	s_add_i32 m0, s53, 0x8000
	v_mov_b32_e32 v188, v191
	global_load_lds_dwordx4 v[130:131], off
	v_mov_b32_e32 v130, v191
	v_mov_b32_e32 v131, v189
	v_lshl_add_u64 v[132:133], s[44:45], 0, v[188:189]
	v_lshl_add_u64 v[132:133], v[132:133], 0, s[10:11]
	s_add_i32 m0, s53, 0x2000
	v_lshl_add_u64 v[130:131], s[46:47], 0, v[130:131]
	global_load_lds_dwordx4 v[132:133], off
	v_lshl_add_u64 v[130:131], v[130:131], 0, s[10:11]
	s_add_i32 m0, s53, 0xa000
	v_mov_b32_e32 v188, v192
	global_load_lds_dwordx4 v[130:131], off
	v_mov_b32_e32 v130, v192
	v_mov_b32_e32 v131, v189
	v_lshl_add_u64 v[132:133], s[44:45], 0, v[188:189]
	v_lshl_add_u64 v[132:133], v[132:133], 0, s[10:11]
	s_add_i32 m0, s53, 0x4000
	v_lshl_add_u64 v[130:131], s[46:47], 0, v[130:131]
	global_load_lds_dwordx4 v[132:133], off
	v_lshl_add_u64 v[130:131], v[130:131], 0, s[10:11]
	s_add_i32 m0, s53, 0xc000
	s_nop 0
	global_load_lds_dwordx4 v[130:131], off
	v_mov_b32_e32 v130, v193
	v_mov_b32_e32 v131, v193
	s_mov_b64 s[44:45], -1
	s_cbranch_execz .LBB0_1047
	s_branch .LBB0_1050

; DEVI f32x4 mfma16(bf16x8 a, bf16x8 b, f32x4 c) { return __builtin_amdgcn_mfma_f32_16x16x32_bf16(a, b, c, 0, 0, 0); }
; template <int MODE, class Epi>
; DEVI void gemm256_phase(int sw, const bf16_t* __restrict__ W, int ldw, const bf16_t* __restrict__ X, int ldx, int K, int nN, char* shm, const Epi& epi) {
;     ...
;     for (int t = 0; t < ntk; ++t) {
;       const int cur = (b0 + t) & 1;
;       const bool st_own = t + 1 < ntk, st_next = !st_own && has_next;
;       if (wid < 4) {
;         if (st_own) stage(cur ^ 1, n0, m0, kt0 + t + 1);
;         else if (st_next) stage(cur ^ 1, n1, m1, kt1);
;       }
;       const char* SAp = shm + cur * STAGE_B + wr * (16 * 1024) + lds_lo;
;       const char* SBp = shm + cur * STAGE_B + TILE_B + wc * (8 * 1024) + lds_lo;
; #pragma unroll
;       for (int ks = 0; ks < 2; ++ks) {
;         const int kx = (wid >> 2) ? (1 - 2 * ks) * 1024 : 0;
;         bf16x8 At[8], Bf[4];
; #pragma unroll
;         for (int m = 0; m < 8; ++m) At[m] = *(const bf16x8*)(SAp + (2 * m + ks) * 1024 + kx);
; #pragma unroll
;         for (int n = 0; n < 4; ++n) Bf[n] = *(const bf16x8*)(SBp + (2 * n + ks) * 1024 + kx);
; #pragma unroll
;         for (int m = 0; m < 8; ++m)
; #pragma unroll
;           for (int n = 0; n < 4; ++n) acc[m][n] = mfma16(At[m], Bf[n], acc[m][n]);
;         __builtin_amdgcn_sched_barrier(0);
;         if (ks == 0 && wid >= 4) {
;           if (st_own) stage(cur ^ 1, n0, m0, kt0 + t + 1);
;           else if (st_next) stage(cur ^ 1, n1, m1, kt1);
;         }
;       }
;       asm volatile("s_waitcnt vmcnt(0)" ::: "memory");
;       __syncthreads();
;     }
.LBB0_1269:
	v_add_u32_e32 v154, s58, v129
	ds_read_b128 v[220:223], v154 offset:1024
	v_add_u32_e32 v128, s58, v128
	ds_read_b128 v[134:137], v128 offset:33792
	ds_read_b128 v[224:227], v154 offset:3072
	ds_read_b128 v[142:145], v128 offset:35840
	ds_read_b128 v[146:149], v128 offset:37888
	ds_read_b128 v[150:153], v128 offset:39936
	ds_read_b128 v[228:231], v154 offset:5120
	ds_read_b128 v[232:235], v154 offset:7168
	s_waitcnt lgkmcnt(2)
	v_mfma_f32_16x16x32_bf16 v[124:127], v[220:223], v[134:137], v[124:127]
	v_mfma_f32_16x16x32_bf16 v[120:123], v[220:223], v[142:145], v[120:123]
	v_mfma_f32_16x16x32_bf16 v[116:119], v[220:223], v[146:149], v[116:119]
	v_mfma_f32_16x16x32_bf16 v[112:115], v[220:223], v[150:153], v[112:115]
	ds_read_b128 v[236:239], v154 offset:9216
	s_waitcnt lgkmcnt(3)
	v_mfma_f32_16x16x32_bf16 v[108:111], v[224:227], v[134:137], v[108:111]
	v_mfma_f32_16x16x32_bf16 v[104:107], v[224:227], v[142:145], v[104:107]
	v_mfma_f32_16x16x32_bf16 v[100:103], v[224:227], v[146:149], v[100:103]
	v_mfma_f32_16x16x32_bf16 v[96:99], v[224:227], v[150:153], v[96:99]
	ds_read_b128 v[240:243], v154 offset:11264
	s_waitcnt lgkmcnt(3)
	v_mfma_f32_16x16x32_bf16 v[92:95], v[228:231], v[134:137], v[92:95]
	v_mfma_f32_16x16x32_bf16 v[88:91], v[228:231], v[142:145], v[88:91]
	v_mfma_f32_16x16x32_bf16 v[84:87], v[228:231], v[146:149], v[84:87]
	v_mfma_f32_16x16x32_bf16 v[80:83], v[228:231], v[150:153], v[80:83]
	ds_read_b128 v[244:247], v154 offset:13312
	s_waitcnt lgkmcnt(3)
	v_mfma_f32_16x16x32_bf16 v[76:79], v[232:235], v[134:137], v[76:79]
	v_mfma_f32_16x16x32_bf16 v[72:75], v[232:235], v[142:145], v[72:75]
	v_mfma_f32_16x16x32_bf16 v[68:71], v[232:235], v[146:149], v[68:71]
	v_mfma_f32_16x16x32_bf16 v[64:67], v[232:235], v[150:153], v[64:67]
	ds_read_b128 v[248:251], v154 offset:15360
	s_waitcnt lgkmcnt(3)
	v_mfma_f32_16x16x32_bf16 v[60:63], v[236:239], v[134:137], v[60:63]
	v_mfma_f32_16x16x32_bf16 v[56:59], v[236:239], v[142:145], v[56:59]
	v_mfma_f32_16x16x32_bf16 v[52:55], v[236:239], v[146:149], v[52:55]
	v_mfma_f32_16x16x32_bf16 v[48:51], v[236:239], v[150:153], v[48:51]
	s_waitcnt lgkmcnt(2)
	v_mfma_f32_16x16x32_bf16 v[44:47], v[240:243], v[134:137], v[44:47]
	v_mfma_f32_16x16x32_bf16 v[40:43], v[240:243], v[142:145], v[40:43]
	v_mfma_f32_16x16x32_bf16 v[36:39], v[240:243], v[146:149], v[36:39]
	v_mfma_f32_16x16x32_bf16 v[32:35], v[240:243], v[150:153], v[32:35]
	s_addk_i32 s72, 0x80
	s_cmp_eq_u32 s71, s73
	s_cbranch_scc1 .Lmy_xexit_1270
	s_add_i32 s0, s49, s73
	s_and_b32 s74, s0, 1
	s_add_i32 s73, s73, 1
	s_cmp_lt_i32 s73, s54
	s_cselect_b64 s[0:1], -1, 0
	s_cmp_ge_i32 s73, s54
	s_cselect_b64 s[8:9], -1, 0
	v_cndmask_b32_e64 v128, 0, 1, s[0:1]
	s_and_b64 s[8:9], s[2:3], s[8:9]
	s_andn2_b64 vcc, exec, s[40:41]
	v_cmp_ne_u32_e64 s[0:1], 1, v128
	s_lshl_b32 s10, s74, 16
	s_add_i32 s11, s10, s55
	v_add_u32_e32 v129, s11, v194
	v_add_u32_e32 v253, s57, v129
	s_or_b32 s11, s10, s56
	v_add_u32_e32 v128, s11, v194
	v_add_u32_e32 v252, s57, v128
	s_waitcnt lgkmcnt(0)
	s_waitcnt vmcnt(0)
	s_barrier
	ds_read_b128 v[220:223], v253
	ds_read_b128 v[224:227], v253 offset:2048
	v_mfma_f32_16x16x32_bf16 v[28:31], v[244:247], v[134:137], v[28:31]
	v_mfma_f32_16x16x32_bf16 v[12:15], v[248:251], v[134:137], v[12:15]
	ds_read_b128 v[134:137], v252 offset:32768
	v_mfma_f32_16x16x32_bf16 v[24:27], v[244:247], v[142:145], v[24:27]
	v_mfma_f32_16x16x32_bf16 v[8:11], v[248:251], v[142:145], v[8:11]
	ds_read_b128 v[142:145], v252 offset:34816
	v_mfma_f32_16x16x32_bf16 v[20:23], v[244:247], v[146:149], v[20:23]
	v_mfma_f32_16x16x32_bf16 v[4:7], v[248:251], v[146:149], v[4:7]
	ds_read_b128 v[146:149], v252 offset:36864
	v_mfma_f32_16x16x32_bf16 v[16:19], v[244:247], v[150:153], v[16:19]
	v_mfma_f32_16x16x32_bf16 v[0:3], v[248:251], v[150:153], v[0:3]
	ds_read_b128 v[150:153], v252 offset:38912
	ds_read_b128 v[228:231], v253 offset:4096
	ds_read_b128 v[232:235], v253 offset:6144
	v_mov_b32_e32 v154, v253
	s_branch .Lmy_xf_1270

; DEVI f32x4 mfma16(bf16x8 a, bf16x8 b, f32x4 c) { return __builtin_amdgcn_mfma_f32_16x16x32_bf16(a, b, c, 0, 0, 0); }
; template <int MODE, class Epi>
; DEVI void gemm256_phase(int sw, const bf16_t* __restrict__ W, int ldw, const bf16_t* __restrict__ X, int ldx, int K, int nN, char* shm, const Epi& epi) {
;     ...
;   auto stage = [&](int buf, int n0, int m0, int kt) {
;     const char* wk = (const char*)(W + (size_t)n0 * ldw) + kt * 128;
;     const char* xk = (const char*)(X + (size_t)m0 * ldx) + kt * 128;
; #pragma unroll
;     for (int i = 0; i < 4; ++i) {
;       unsigned ow = offW[i], ox = offX[i];
;       asm volatile("" : "+v"(ow), "+v"(ox));
;       __builtin_amdgcn_global_load_lds((const unsigned*)(wk + ow), (unsigned*)(shm + buf * STAGE_B + wid * 1024 + i * 8192), 16, 0, 0);
;       __builtin_amdgcn_global_load_lds((const unsigned*)(xk + ox), (unsigned*)(shm + buf * STAGE_B + TILE_B + wid * 1024 + i * 8192), 16, 0, 0);
;     }
;     ...
;       for (int ks = 0; ks < 2; ++ks) {
;         const int kx = (wid >> 2) ? (1 - 2 * ks) * 1024 : 0;
;         bf16x8 At[8], Bf[4];
; #pragma unroll
;         for (int m = 0; m < 8; ++m) At[m] = *(const bf16x8*)(SAp + (2 * m + ks) * 1024 + kx);
; #pragma unroll
;         for (int n = 0; n < 4; ++n) Bf[n] = *(const bf16x8*)(SBp + (2 * n + ks) * 1024 + kx);
; #pragma unroll
;         for (int m = 0; m < 8; ++m)
; #pragma unroll
;           for (int n = 0; n < 4; ++n) acc[m][n] = mfma16(At[m], Bf[n], acc[m][n]);
;         __builtin_amdgcn_sched_barrier(0);
;         if (ks == 0 && wid >= 4) {
;           if (st_own) stage(cur ^ 1, n0, m0, kt0 + t + 1);
;           else if (st_next) stage(cur ^ 1, n1, m1, kt1);
;         }
.Lmy_xf_1270:
	s_add_u32 s98, s67, s72
	s_addc_u32 s99, s68, 0
	s_add_u32 s98, s98, 0x80
	s_addc_u32 s99, s99, 0
	s_add_u32 s100, s69, s72
	s_addc_u32 s101, s70, 0
	s_add_u32 s100, s100, 0x80
	s_addc_u32 s101, s101, 0
	s_xor_b32 m0, s10, 0x10000
	s_add_i32 m0, m0, s48
	s_waitcnt lgkmcnt(2)
	v_mfma_f32_16x16x32_bf16 v[124:127], v[220:223], v[134:137], v[124:127]
	v_mfma_f32_16x16x32_bf16 v[120:123], v[220:223], v[142:145], v[120:123]
	v_mfma_f32_16x16x32_bf16 v[116:119], v[220:223], v[146:149], v[116:119]
	v_mfma_f32_16x16x32_bf16 v[112:115], v[220:223], v[150:153], v[112:115]
	global_load_lds_dwordx4 v190, s[98:99]
	ds_read_b128 v[236:239], v154 offset:8192
	s_add_i32 m0, m0, 0x8000
	s_waitcnt lgkmcnt(3)
	v_mfma_f32_16x16x32_bf16 v[108:111], v[224:227], v[134:137], v[108:111]
	v_mfma_f32_16x16x32_bf16 v[104:107], v[224:227], v[142:145], v[104:107]
	v_mfma_f32_16x16x32_bf16 v[100:103], v[224:227], v[146:149], v[100:103]
	v_mfma_f32_16x16x32_bf16 v[96:99], v[224:227], v[150:153], v[96:99]
	global_load_lds_dwordx4 v190, s[100:101]
	ds_read_b128 v[240:243], v154 offset:10240
	s_add_i32 m0, m0, 0xffffa000
	s_waitcnt lgkmcnt(3)
	v_mfma_f32_16x16x32_bf16 v[92:95], v[228:231], v[134:137], v[92:95]
	v_mfma_f32_16x16x32_bf16 v[88:91], v[228:231], v[142:145], v[88:91]
	v_mfma_f32_16x16x32_bf16 v[84:87], v[228:231], v[146:149], v[84:87]
	v_mfma_f32_16x16x32_bf16 v[80:83], v[228:231], v[150:153], v[80:83]
	global_load_lds_dwordx4 v191, s[98:99]
	ds_read_b128 v[244:247], v154 offset:12288
	s_add_i32 m0, m0, 0x8000
	s_waitcnt lgkmcnt(3)
	v_mfma_f32_16x16x32_bf16 v[76:79], v[232:235], v[134:137], v[76:79]
	v_mfma_f32_16x16x32_bf16 v[72:75], v[232:235], v[142:145], v[72:75]
	v_mfma_f32_16x16x32_bf16 v[68:71], v[232:235], v[146:149], v[68:71]
	v_mfma_f32_16x16x32_bf16 v[64:67], v[232:235], v[150:153], v[64:67]
	global_load_lds_dwordx4 v191, s[100:101]
	ds_read_b128 v[248:251], v154 offset:14336
	s_add_i32 m0, m0, 0xffffa000
	s_waitcnt lgkmcnt(3)
	v_mfma_f32_16x16x32_bf16 v[60:63], v[236:239], v[134:137], v[60:63]
	v_mfma_f32_16x16x32_bf16 v[56:59], v[236:239], v[142:145], v[56:59]
	v_mfma_f32_16x16x32_bf16 v[52:55], v[236:239], v[146:149], v[52:55]
	v_mfma_f32_16x16x32_bf16 v[48:51], v[236:239], v[150:153], v[48:51]
	global_load_lds_dwordx4 v192, s[98:99]
	s_add_i32 m0, m0, 0x8000
	s_waitcnt lgkmcnt(2)
	v_mfma_f32_16x16x32_bf16 v[44:47], v[240:243], v[134:137], v[44:47]
	v_mfma_f32_16x16x32_bf16 v[40:43], v[240:243], v[142:145], v[40:43]
	v_mfma_f32_16x16x32_bf16 v[36:39], v[240:243], v[146:149], v[36:39]
	v_mfma_f32_16x16x32_bf16 v[32:35], v[240:243], v[150:153], v[32:35]
	global_load_lds_dwordx4 v192, s[100:101]
	s_add_i32 m0, m0, 0xffffa000
	s_waitcnt lgkmcnt(1)
	v_mfma_f32_16x16x32_bf16 v[28:31], v[244:247], v[134:137], v[28:31]
	v_mfma_f32_16x16x32_bf16 v[24:27], v[244:247], v[142:145], v[24:27]
	v_mfma_f32_16x16x32_bf16 v[20:23], v[244:247], v[146:149], v[20:23]
	v_mfma_f32_16x16x32_bf16 v[16:19], v[244:247], v[150:153], v[16:19]
	global_load_lds_dwordx4 v193, s[98:99]
	s_add_i32 m0, m0, 0x8000
	s_waitcnt lgkmcnt(0)
	v_mfma_f32_16x16x32_bf16 v[12:15], v[248:251], v[134:137], v[12:15]
	v_mfma_f32_16x16x32_bf16 v[8:11], v[248:251], v[142:145], v[8:11]
	v_mfma_f32_16x16x32_bf16 v[4:7], v[248:251], v[146:149], v[4:7]
	v_mfma_f32_16x16x32_bf16 v[0:3], v[248:251], v[150:153], v[0:3]
	global_load_lds_dwordx4 v193, s[100:101]
	s_andn2_b64 vcc, exec, s[38:39]
	s_branch .LBB0_1269
	s_and_b64 vcc, exec, s[0:1]
	s_xor_b32 s46, s10, 0x10000
	s_cbranch_vccnz .LBB0_1282
	s_ashr_i32 s10, s72, 31
	s_add_u32 s12, s67, s72
	s_addc_u32 s13, s68, s10
	s_add_u32 s0, s12, 0x80
	s_addc_u32 s1, s13, 0
	s_add_u32 s14, s69, s72
	s_addc_u32 s15, s70, s10
	s_add_u32 s10, s14, 0x80
	v_mov_b32_e32 v130, v190
	v_mov_b32_e32 v188, v190
	s_addc_u32 s11, s15, 0
	s_add_i32 s47, s48, s46
	v_lshl_add_u64 v[132:133], s[12:13], 0, v[188:189]
	v_mov_b32_e32 v131, v189
	v_lshl_add_u64 v[132:133], v[132:133], 0, s[42:43]
	s_mov_b32 m0, s47
	v_lshl_add_u64 v[130:131], s[14:15], 0, v[130:131]
	global_load_lds_dwordx4 v[132:133], off
	v_lshl_add_u64 v[130:131], v[130:131], 0, s[42:43]
	s_add_i32 m0, s47, 0x8000
	v_mov_b32_e32 v188, v191
	global_load_lds_dwordx4 v[130:131], off
	v_mov_b32_e32 v130, v191
	v_mov_b32_e32 v131, v189
	v_lshl_add_u64 v[132:133], s[12:13], 0, v[188:189]
	v_lshl_add_u64 v[132:133], v[132:133], 0, s[42:43]
	s_add_i32 m0, s47, 0x2000
	v_lshl_add_u64 v[130:131], s[14:15], 0, v[130:131]
	global_load_lds_dwordx4 v[132:133], off
	v_lshl_add_u64 v[130:131], v[130:131], 0, s[42:43]
	s_add_i32 m0, s47, 0xa000
	v_mov_b32_e32 v188, v192
	global_load_lds_dwordx4 v[130:131], off
	v_mov_b32_e32 v130, v192
	v_mov_b32_e32 v131, v189
	v_lshl_add_u64 v[132:133], s[12:13], 0, v[188:189]
	v_lshl_add_u64 v[132:133], v[132:133], 0, s[42:43]
	s_add_i32 m0, s47, 0x4000
	v_lshl_add_u64 v[130:131], s[14:15], 0, v[130:131]
	global_load_lds_dwordx4 v[132:133], off
	v_lshl_add_u64 v[130:131], v[130:131], 0, s[42:43]
	s_add_i32 m0, s47, 0xc000
	s_nop 0
	global_load_lds_dwordx4 v[130:131], off
	v_mov_b32_e32 v130, v193
	v_mov_b32_e32 v131, v193
	s_mov_b64 s[12:13], -1
	s_cbranch_execz .LBB0_1283
	s_branch .LBB0_1286

; DEVI f32x4 mfma16(bf16x8 a, bf16x8 b, f32x4 c) { return __builtin_amdgcn_mfma_f32_16x16x32_bf16(a, b, c, 0, 0, 0); }
; template <int MODE, class Epi>
; DEVI void gemm256_phase(int sw, const bf16_t* __restrict__ W, int ldw, const bf16_t* __restrict__ X, int ldx, int K, int nN, char* shm, const Epi& epi) {
;     ...
;     for (int t = 0; t < ntk; ++t) {
;       const int cur = (b0 + t) & 1;
;       const bool st_own = t + 1 < ntk, st_next = !st_own && has_next;
;       if (wid < 4) {
;         if (st_own) stage(cur ^ 1, n0, m0, kt0 + t + 1);
;         else if (st_next) stage(cur ^ 1, n1, m1, kt1);
;       }
;       const char* SAp = shm + cur * STAGE_B + wr * (16 * 1024) + lds_lo;
;       const char* SBp = shm + cur * STAGE_B + TILE_B + wc * (8 * 1024) + lds_lo;
; #pragma unroll
;       for (int ks = 0; ks < 2; ++ks) {
;         const int kx = (wid >> 2) ? (1 - 2 * ks) * 1024 : 0;
;         bf16x8 At[8], Bf[4];
; #pragma unroll
;         for (int m = 0; m < 8; ++m) At[m] = *(const bf16x8*)(SAp + (2 * m + ks) * 1024 + kx);
; #pragma unroll
;         for (int n = 0; n < 4; ++n) Bf[n] = *(const bf16x8*)(SBp + (2 * n + ks) * 1024 + kx);
; #pragma unroll
;         for (int m = 0; m < 8; ++m)
; #pragma unroll
;           for (int n = 0; n < 4; ++n) acc[m][n] = mfma16(At[m], Bf[n], acc[m][n]);
;         __builtin_amdgcn_sched_barrier(0);
;         if (ks == 0 && wid >= 4) {
;           if (st_own) stage(cur ^ 1, n0, m0, kt0 + t + 1);
;           else if (st_next) stage(cur ^ 1, n1, m1, kt1);
;         }
;       }
;       asm volatile("s_waitcnt vmcnt(0)" ::: "memory");
;       __syncthreads();
;     }
.LBB0_1677:
	v_add_u32_e32 v154, s63, v129
	ds_read_b128 v[220:223], v154 offset:1024
	v_add_u32_e32 v128, s63, v128
	ds_read_b128 v[134:137], v128 offset:33792
	ds_read_b128 v[224:227], v154 offset:3072
	ds_read_b128 v[142:145], v128 offset:35840
	ds_read_b128 v[146:149], v128 offset:37888
	ds_read_b128 v[150:153], v128 offset:39936
	ds_read_b128 v[228:231], v154 offset:5120
	ds_read_b128 v[232:235], v154 offset:7168
	s_waitcnt lgkmcnt(2)
	v_mfma_f32_16x16x32_bf16 v[124:127], v[220:223], v[134:137], v[124:127]
	v_mfma_f32_16x16x32_bf16 v[120:123], v[220:223], v[142:145], v[120:123]
	v_mfma_f32_16x16x32_bf16 v[116:119], v[220:223], v[146:149], v[116:119]
	v_mfma_f32_16x16x32_bf16 v[112:115], v[220:223], v[150:153], v[112:115]
	ds_read_b128 v[236:239], v154 offset:9216
	s_waitcnt lgkmcnt(3)
	v_mfma_f32_16x16x32_bf16 v[108:111], v[224:227], v[134:137], v[108:111]
	v_mfma_f32_16x16x32_bf16 v[104:107], v[224:227], v[142:145], v[104:107]
	v_mfma_f32_16x16x32_bf16 v[100:103], v[224:227], v[146:149], v[100:103]
	v_mfma_f32_16x16x32_bf16 v[96:99], v[224:227], v[150:153], v[96:99]
	ds_read_b128 v[240:243], v154 offset:11264
	s_waitcnt lgkmcnt(3)
	v_mfma_f32_16x16x32_bf16 v[92:95], v[228:231], v[134:137], v[92:95]
	v_mfma_f32_16x16x32_bf16 v[88:91], v[228:231], v[142:145], v[88:91]
	v_mfma_f32_16x16x32_bf16 v[84:87], v[228:231], v[146:149], v[84:87]
	v_mfma_f32_16x16x32_bf16 v[80:83], v[228:231], v[150:153], v[80:83]
	ds_read_b128 v[244:247], v154 offset:13312
	s_waitcnt lgkmcnt(3)
	v_mfma_f32_16x16x32_bf16 v[76:79], v[232:235], v[134:137], v[76:79]
	v_mfma_f32_16x16x32_bf16 v[72:75], v[232:235], v[142:145], v[72:75]
	v_mfma_f32_16x16x32_bf16 v[68:71], v[232:235], v[146:149], v[68:71]
	v_mfma_f32_16x16x32_bf16 v[64:67], v[232:235], v[150:153], v[64:67]
	ds_read_b128 v[248:251], v154 offset:15360
	s_waitcnt lgkmcnt(3)
	v_mfma_f32_16x16x32_bf16 v[60:63], v[236:239], v[134:137], v[60:63]
	v_mfma_f32_16x16x32_bf16 v[56:59], v[236:239], v[142:145], v[56:59]
	v_mfma_f32_16x16x32_bf16 v[52:55], v[236:239], v[146:149], v[52:55]
	v_mfma_f32_16x16x32_bf16 v[48:51], v[236:239], v[150:153], v[48:51]
	s_waitcnt lgkmcnt(2)
	v_mfma_f32_16x16x32_bf16 v[44:47], v[240:243], v[134:137], v[44:47]
	v_mfma_f32_16x16x32_bf16 v[40:43], v[240:243], v[142:145], v[40:43]
	v_mfma_f32_16x16x32_bf16 v[36:39], v[240:243], v[146:149], v[36:39]
	v_mfma_f32_16x16x32_bf16 v[32:35], v[240:243], v[150:153], v[32:35]
	s_addk_i32 s78, 0x80
	s_cmp_eq_u32 s77, s79
	s_cbranch_scc1 .Lmy_xexit_1678
	s_add_i32 s2, s61, s79
	s_and_b32 s80, s2, 1
	s_add_i32 s79, s79, 1
	s_cmp_lt_i32 s79, s60
	s_cselect_b64 s[2:3], -1, 0
	s_cmp_ge_i32 s79, s60
	s_cselect_b64 s[40:41], -1, 0
	v_cndmask_b32_e64 v128, 0, 1, s[2:3]
	s_and_b64 s[40:41], s[34:35], s[40:41]
	s_and_b64 vcc, exec, s[0:1]
	v_cmp_ne_u32_e64 s[2:3], 1, v128
	s_lshl_b32 s42, s80, 16
	s_add_i32 s16, s42, s57
	v_add_u32_e32 v129, s16, v194
	v_add_u32_e32 v253, s62, v129
	s_or_b32 s16, s42, s58
	v_add_u32_e32 v128, s16, v194
	v_add_u32_e32 v252, s62, v128
	s_waitcnt lgkmcnt(0)
	s_waitcnt vmcnt(0)
	s_barrier
	ds_read_b128 v[220:223], v253
	ds_read_b128 v[224:227], v253 offset:2048
	v_mfma_f32_16x16x32_bf16 v[28:31], v[244:247], v[134:137], v[28:31]
	v_mfma_f32_16x16x32_bf16 v[12:15], v[248:251], v[134:137], v[12:15]
	ds_read_b128 v[134:137], v252 offset:32768
	v_mfma_f32_16x16x32_bf16 v[24:27], v[244:247], v[142:145], v[24:27]
	v_mfma_f32_16x16x32_bf16 v[8:11], v[248:251], v[142:145], v[8:11]
	ds_read_b128 v[142:145], v252 offset:34816
	v_mfma_f32_16x16x32_bf16 v[20:23], v[244:247], v[146:149], v[20:23]
	v_mfma_f32_16x16x32_bf16 v[4:7], v[248:251], v[146:149], v[4:7]
	ds_read_b128 v[146:149], v252 offset:36864
	v_mfma_f32_16x16x32_bf16 v[16:19], v[244:247], v[150:153], v[16:19]
	v_mfma_f32_16x16x32_bf16 v[0:3], v[248:251], v[150:153], v[0:3]
	ds_read_b128 v[150:153], v252 offset:38912
	ds_read_b128 v[228:231], v253 offset:4096
	ds_read_b128 v[232:235], v253 offset:6144
	v_mov_b32_e32 v154, v253
	s_branch .Lmy_xf_1678

; DEVI f32x4 mfma16(bf16x8 a, bf16x8 b, f32x4 c) { return __builtin_amdgcn_mfma_f32_16x16x32_bf16(a, b, c, 0, 0, 0); }
; template <int MODE, class Epi>
; DEVI void gemm256_phase(int sw, const bf16_t* __restrict__ W, int ldw, const bf16_t* __restrict__ X, int ldx, int K, int nN, char* shm, const Epi& epi) {
;     ...
;   auto stage = [&](int buf, int n0, int m0, int kt) {
;     const char* wk = (const char*)(W + (size_t)n0 * ldw) + kt * 128;
;     const char* xk = (const char*)(X + (size_t)m0 * ldx) + kt * 128;
; #pragma unroll
;     for (int i = 0; i < 4; ++i) {
;       unsigned ow = offW[i], ox = offX[i];
;       asm volatile("" : "+v"(ow), "+v"(ox));
;       __builtin_amdgcn_global_load_lds((const unsigned*)(wk + ow), (unsigned*)(shm + buf * STAGE_B + wid * 1024 + i * 8192), 16, 0, 0);
;       __builtin_amdgcn_global_load_lds((const unsigned*)(xk + ox), (unsigned*)(shm + buf * STAGE_B + TILE_B + wid * 1024 + i * 8192), 16, 0, 0);
;     }
;     ...
;       for (int ks = 0; ks < 2; ++ks) {
;         const int kx = (wid >> 2) ? (1 - 2 * ks) * 1024 : 0;
;         bf16x8 At[8], Bf[4];
; #pragma unroll
;         for (int m = 0; m < 8; ++m) At[m] = *(const bf16x8*)(SAp + (2 * m + ks) * 1024 + kx);
; #pragma unroll
;         for (int n = 0; n < 4; ++n) Bf[n] = *(const bf16x8*)(SBp + (2 * n + ks) * 1024 + kx);
; #pragma unroll
;         for (int m = 0; m < 8; ++m)
; #pragma unroll
;           for (int n = 0; n < 4; ++n) acc[m][n] = mfma16(At[m], Bf[n], acc[m][n]);
;         __builtin_amdgcn_sched_barrier(0);
;         if (ks == 0 && wid >= 4) {
;           if (st_own) stage(cur ^ 1, n0, m0, kt0 + t + 1);
;           else if (st_next) stage(cur ^ 1, n1, m1, kt1);
;         }
.Lmy_xf_1678:
	s_add_u32 s98, s73, s78
	s_addc_u32 s99, s74, 0
	s_add_u32 s98, s98, 0x80
	s_addc_u32 s99, s99, 0
	s_add_u32 s100, s75, s78
	s_addc_u32 s101, s76, 0
	s_add_u32 s100, s100, 0x80
	s_addc_u32 s101, s101, 0
	s_xor_b32 m0, s42, 0x10000
	s_add_i32 m0, m0, s56
	s_waitcnt lgkmcnt(2)
	v_mfma_f32_16x16x32_bf16 v[124:127], v[220:223], v[134:137], v[124:127]
	v_mfma_f32_16x16x32_bf16 v[120:123], v[220:223], v[142:145], v[120:123]
	v_mfma_f32_16x16x32_bf16 v[116:119], v[220:223], v[146:149], v[116:119]
	v_mfma_f32_16x16x32_bf16 v[112:115], v[220:223], v[150:153], v[112:115]
	global_load_lds_dwordx4 v190, s[98:99]
	ds_read_b128 v[236:239], v154 offset:8192
	s_add_i32 m0, m0, 0x8000
	s_waitcnt lgkmcnt(3)
	v_mfma_f32_16x16x32_bf16 v[108:111], v[224:227], v[134:137], v[108:111]
	v_mfma_f32_16x16x32_bf16 v[104:107], v[224:227], v[142:145], v[104:107]
	v_mfma_f32_16x16x32_bf16 v[100:103], v[224:227], v[146:149], v[100:103]
	v_mfma_f32_16x16x32_bf16 v[96:99], v[224:227], v[150:153], v[96:99]
	global_load_lds_dwordx4 v190, s[100:101]
	ds_read_b128 v[240:243], v154 offset:10240
	s_add_i32 m0, m0, 0xffffa000
	s_waitcnt lgkmcnt(3)
	v_mfma_f32_16x16x32_bf16 v[92:95], v[228:231], v[134:137], v[92:95]
	v_mfma_f32_16x16x32_bf16 v[88:91], v[228:231], v[142:145], v[88:91]
	v_mfma_f32_16x16x32_bf16 v[84:87], v[228:231], v[146:149], v[84:87]
	v_mfma_f32_16x16x32_bf16 v[80:83], v[228:231], v[150:153], v[80:83]
	global_load_lds_dwordx4 v191, s[98:99]
	ds_read_b128 v[244:247], v154 offset:12288
	s_add_i32 m0, m0, 0x8000
	s_waitcnt lgkmcnt(3)
	v_mfma_f32_16x16x32_bf16 v[76:79], v[232:235], v[134:137], v[76:79]
	v_mfma_f32_16x16x32_bf16 v[72:75], v[232:235], v[142:145], v[72:75]
	v_mfma_f32_16x16x32_bf16 v[68:71], v[232:235], v[146:149], v[68:71]
	v_mfma_f32_16x16x32_bf16 v[64:67], v[232:235], v[150:153], v[64:67]
	global_load_lds_dwordx4 v191, s[100:101]
	ds_read_b128 v[248:251], v154 offset:14336
	s_add_i32 m0, m0, 0xffffa000
	s_waitcnt lgkmcnt(3)
	v_mfma_f32_16x16x32_bf16 v[60:63], v[236:239], v[134:137], v[60:63]
	v_mfma_f32_16x16x32_bf16 v[56:59], v[236:239], v[142:145], v[56:59]
	v_mfma_f32_16x16x32_bf16 v[52:55], v[236:239], v[146:149], v[52:55]
	v_mfma_f32_16x16x32_bf16 v[48:51], v[236:239], v[150:153], v[48:51]
	global_load_lds_dwordx4 v192, s[98:99]
	s_add_i32 m0, m0, 0x8000
	s_waitcnt lgkmcnt(2)
	v_mfma_f32_16x16x32_bf16 v[44:47], v[240:243], v[134:137], v[44:47]
	v_mfma_f32_16x16x32_bf16 v[40:43], v[240:243], v[142:145], v[40:43]
	v_mfma_f32_16x16x32_bf16 v[36:39], v[240:243], v[146:149], v[36:39]
	v_mfma_f32_16x16x32_bf16 v[32:35], v[240:243], v[150:153], v[32:35]
	global_load_lds_dwordx4 v192, s[100:101]
	s_add_i32 m0, m0, 0xffffa000
	s_waitcnt lgkmcnt(1)
	v_mfma_f32_16x16x32_bf16 v[28:31], v[244:247], v[134:137], v[28:31]
	v_mfma_f32_16x16x32_bf16 v[24:27], v[244:247], v[142:145], v[24:27]
	v_mfma_f32_16x16x32_bf16 v[20:23], v[244:247], v[146:149], v[20:23]
	v_mfma_f32_16x16x32_bf16 v[16:19], v[244:247], v[150:153], v[16:19]
	global_load_lds_dwordx4 v193, s[98:99]
	s_add_i32 m0, m0, 0x8000
	s_waitcnt lgkmcnt(0)
	v_mfma_f32_16x16x32_bf16 v[12:15], v[248:251], v[134:137], v[12:15]
	v_mfma_f32_16x16x32_bf16 v[8:11], v[248:251], v[142:145], v[8:11]
	v_mfma_f32_16x16x32_bf16 v[4:7], v[248:251], v[146:149], v[4:7]
	v_mfma_f32_16x16x32_bf16 v[0:3], v[248:251], v[150:153], v[0:3]
	global_load_lds_dwordx4 v193, s[100:101]
	s_andn2_b64 vcc, exec, s[8:9]
	s_branch .LBB0_1677
	s_and_b64 vcc, exec, s[2:3]
	s_xor_b32 s48, s42, 0x10000
	s_cbranch_vccnz .LBB0_1690
	s_ashr_i32 s16, s78, 31
	s_add_u32 s44, s73, s78
	s_addc_u32 s45, s74, s16
	s_add_u32 s2, s44, 0x80
	s_addc_u32 s3, s45, 0
	s_add_u32 s46, s75, s78
	s_addc_u32 s47, s76, s16
	s_add_u32 s42, s46, 0x80
	v_mov_b32_e32 v130, v190
	v_mov_b32_e32 v188, v190
	s_addc_u32 s43, s47, 0
	s_add_i32 s16, s56, s48
	v_lshl_add_u64 v[132:133], s[44:45], 0, v[188:189]
	v_mov_b32_e32 v131, v189
	v_lshl_add_u64 v[132:133], v[132:133], 0, s[12:13]
	s_mov_b32 m0, s16
	v_lshl_add_u64 v[130:131], s[46:47], 0, v[130:131]
	global_load_lds_dwordx4 v[132:133], off
	v_lshl_add_u64 v[130:131], v[130:131], 0, s[12:13]
	s_add_i32 m0, s16, 0x8000
	v_mov_b32_e32 v188, v191
	global_load_lds_dwordx4 v[130:131], off
	v_mov_b32_e32 v130, v191
	v_mov_b32_e32 v131, v189
	v_lshl_add_u64 v[132:133], s[44:45], 0, v[188:189]
	v_lshl_add_u64 v[132:133], v[132:133], 0, s[12:13]
	s_add_i32 m0, s16, 0x2000
	v_lshl_add_u64 v[130:131], s[46:47], 0, v[130:131]
	global_load_lds_dwordx4 v[132:133], off
	v_lshl_add_u64 v[130:131], v[130:131], 0, s[12:13]
	s_add_i32 m0, s16, 0xa000
	v_mov_b32_e32 v188, v192
	global_load_lds_dwordx4 v[130:131], off
	v_mov_b32_e32 v130, v192
	v_mov_b32_e32 v131, v189
	v_lshl_add_u64 v[132:133], s[44:45], 0, v[188:189]
	v_lshl_add_u64 v[132:133], v[132:133], 0, s[12:13]
	s_add_i32 m0, s16, 0x4000
	v_lshl_add_u64 v[130:131], s[46:47], 0, v[130:131]
	global_load_lds_dwordx4 v[132:133], off
	v_lshl_add_u64 v[130:131], v[130:131], 0, s[12:13]
	s_add_i32 m0, s16, 0xc000
	s_nop 0
	global_load_lds_dwordx4 v[130:131], off
	v_mov_b32_e32 v130, v193
	v_mov_b32_e32 v131, v193
	s_mov_b64 s[44:45], -1
	s_cbranch_execz .LBB0_1691
	s_branch .LBB0_1694

; DEVI f32x4 mfma16(bf16x8 a, bf16x8 b, f32x4 c) { return __builtin_amdgcn_mfma_f32_16x16x32_bf16(a, b, c, 0, 0, 0); }
; template <int MODE, class Epi>
; DEVI void gemm256_phase(int sw, const bf16_t* __restrict__ W, int ldw, const bf16_t* __restrict__ X, int ldx, int K, int nN, char* shm, const Epi& epi) {
;     ...
;     for (int t = 0; t < ntk; ++t) {
;       const int cur = (b0 + t) & 1;
;       const bool st_own = t + 1 < ntk, st_next = !st_own && has_next;
;       if (wid < 4) {
;         if (st_own) stage(cur ^ 1, n0, m0, kt0 + t + 1);
;         else if (st_next) stage(cur ^ 1, n1, m1, kt1);
;       }
;       const char* SAp = shm + cur * STAGE_B + wr * (16 * 1024) + lds_lo;
;       const char* SBp = shm + cur * STAGE_B + TILE_B + wc * (8 * 1024) + lds_lo;
; #pragma unroll
;       for (int ks = 0; ks < 2; ++ks) {
;         const int kx = (wid >> 2) ? (1 - 2 * ks) * 1024 : 0;
;         bf16x8 At[8], Bf[4];
; #pragma unroll
;         for (int m = 0; m < 8; ++m) At[m] = *(const bf16x8*)(SAp + (2 * m + ks) * 1024 + kx);
; #pragma unroll
;         for (int n = 0; n < 4; ++n) Bf[n] = *(const bf16x8*)(SBp + (2 * n + ks) * 1024 + kx);
; #pragma unroll
;         for (int m = 0; m < 8; ++m)
; #pragma unroll
;           for (int n = 0; n < 4; ++n) acc[m][n] = mfma16(At[m], Bf[n], acc[m][n]);
;         __builtin_amdgcn_sched_barrier(0);
;         if (ks == 0 && wid >= 4) {
;           if (st_own) stage(cur ^ 1, n0, m0, kt0 + t + 1);
;           else if (st_next) stage(cur ^ 1, n1, m1, kt1);
;         }
;       }
;       asm volatile("s_waitcnt vmcnt(0)" ::: "memory");
;       __syncthreads();
;     }
.LBB0_1759:
	v_add_u32_e32 v154, s38, v129
	ds_read_b128 v[220:223], v154 offset:1024
	v_add_u32_e32 v128, s38, v128
	ds_read_b128 v[134:137], v128 offset:33792
	ds_read_b128 v[224:227], v154 offset:3072
	ds_read_b128 v[142:145], v128 offset:35840
	ds_read_b128 v[146:149], v128 offset:37888
	ds_read_b128 v[150:153], v128 offset:39936
	s_add_i32 s50, s50, 1
	ds_read_b128 v[228:231], v154 offset:5120
	ds_read_b128 v[232:235], v154 offset:7168
	s_waitcnt lgkmcnt(2)
	v_mfma_f32_16x16x32_bf16 v[124:127], v[220:223], v[134:137], v[124:127]
	v_mfma_f32_16x16x32_bf16 v[120:123], v[220:223], v[142:145], v[120:123]
	v_mfma_f32_16x16x32_bf16 v[116:119], v[220:223], v[146:149], v[116:119]
	v_mfma_f32_16x16x32_bf16 v[112:115], v[220:223], v[150:153], v[112:115]
	ds_read_b128 v[236:239], v154 offset:9216
	s_waitcnt lgkmcnt(3)
	v_mfma_f32_16x16x32_bf16 v[108:111], v[224:227], v[134:137], v[108:111]
	v_mfma_f32_16x16x32_bf16 v[104:107], v[224:227], v[142:145], v[104:107]
	v_mfma_f32_16x16x32_bf16 v[100:103], v[224:227], v[146:149], v[100:103]
	v_mfma_f32_16x16x32_bf16 v[96:99], v[224:227], v[150:153], v[96:99]
	ds_read_b128 v[240:243], v154 offset:11264
	s_waitcnt lgkmcnt(3)
	v_mfma_f32_16x16x32_bf16 v[92:95], v[228:231], v[134:137], v[92:95]
	v_mfma_f32_16x16x32_bf16 v[88:91], v[228:231], v[142:145], v[88:91]
	v_mfma_f32_16x16x32_bf16 v[84:87], v[228:231], v[146:149], v[84:87]
	v_mfma_f32_16x16x32_bf16 v[80:83], v[228:231], v[150:153], v[80:83]
	ds_read_b128 v[244:247], v154 offset:13312
	s_waitcnt lgkmcnt(3)
	v_mfma_f32_16x16x32_bf16 v[76:79], v[232:235], v[134:137], v[76:79]
	v_mfma_f32_16x16x32_bf16 v[72:75], v[232:235], v[142:145], v[72:75]
	v_mfma_f32_16x16x32_bf16 v[68:71], v[232:235], v[146:149], v[68:71]
	v_mfma_f32_16x16x32_bf16 v[64:67], v[232:235], v[150:153], v[64:67]
	ds_read_b128 v[248:251], v154 offset:15360
	s_waitcnt lgkmcnt(3)
	v_mfma_f32_16x16x32_bf16 v[60:63], v[236:239], v[134:137], v[60:63]
	v_mfma_f32_16x16x32_bf16 v[56:59], v[236:239], v[142:145], v[56:59]
	v_mfma_f32_16x16x32_bf16 v[52:55], v[236:239], v[146:149], v[52:55]
	v_mfma_f32_16x16x32_bf16 v[48:51], v[236:239], v[150:153], v[48:51]
	s_waitcnt lgkmcnt(2)
	v_mfma_f32_16x16x32_bf16 v[44:47], v[240:243], v[134:137], v[44:47]
	v_mfma_f32_16x16x32_bf16 v[40:43], v[240:243], v[142:145], v[40:43]
	v_mfma_f32_16x16x32_bf16 v[36:39], v[240:243], v[146:149], v[36:39]
	v_mfma_f32_16x16x32_bf16 v[32:35], v[240:243], v[150:153], v[32:35]
	s_addk_i32 s49, 0x80
	s_cmp_eq_u32 s46, s50
	s_cbranch_scc1 .Lmy_xexit_1760
	s_add_i32 s10, s31, s50
	s_and_b32 s52, s10, 1
	s_mov_b64 s[10:11], -1
	s_and_b64 vcc, exec, s[4:5]
	s_lshl_b32 s51, s52, 16
	s_add_i32 s10, s51, s34
	v_add_u32_e32 v129, s10, v198
	v_add_u32_e32 v253, s37, v129
	s_add_i32 s10, s51, s35
	v_add_u32_e32 v128, s10, v198
	v_add_u32_e32 v252, s37, v128
	s_waitcnt lgkmcnt(0)
	s_waitcnt vmcnt(0)
	s_barrier
	ds_read_b128 v[220:223], v253
	ds_read_b128 v[224:227], v253 offset:2048
	v_mfma_f32_16x16x32_bf16 v[28:31], v[244:247], v[134:137], v[28:31]
	v_mfma_f32_16x16x32_bf16 v[12:15], v[248:251], v[134:137], v[12:15]
	ds_read_b128 v[134:137], v252 offset:32768
	v_mfma_f32_16x16x32_bf16 v[24:27], v[244:247], v[142:145], v[24:27]
	v_mfma_f32_16x16x32_bf16 v[8:11], v[248:251], v[142:145], v[8:11]
	ds_read_b128 v[142:145], v252 offset:34816
	v_mfma_f32_16x16x32_bf16 v[20:23], v[244:247], v[146:149], v[20:23]
	v_mfma_f32_16x16x32_bf16 v[4:7], v[248:251], v[146:149], v[4:7]
	ds_read_b128 v[146:149], v252 offset:36864
	v_mfma_f32_16x16x32_bf16 v[16:19], v[244:247], v[150:153], v[16:19]
	v_mfma_f32_16x16x32_bf16 v[0:3], v[248:251], v[150:153], v[0:3]
	ds_read_b128 v[150:153], v252 offset:38912
	ds_read_b128 v[228:231], v253 offset:4096
	ds_read_b128 v[232:235], v253 offset:6144
	v_mov_b32_e32 v154, v253
	s_branch .Lmy_xf_1760

; DEVI f32x4 mfma16(bf16x8 a, bf16x8 b, f32x4 c) { return __builtin_amdgcn_mfma_f32_16x16x32_bf16(a, b, c, 0, 0, 0); }
; template <int MODE, class Epi>
; DEVI void gemm256_phase(int sw, const bf16_t* __restrict__ W, int ldw, const bf16_t* __restrict__ X, int ldx, int K, int nN, char* shm, const Epi& epi) {
;     ...
;   auto stage = [&](int buf, int n0, int m0, int kt) {
;     const char* wk = (const char*)(W + (size_t)n0 * ldw) + kt * 128;
;     const char* xk = (const char*)(X + (size_t)m0 * ldx) + kt * 128;
; #pragma unroll
;     for (int i = 0; i < 4; ++i) {
;       unsigned ow = offW[i], ox = offX[i];
;       asm volatile("" : "+v"(ow), "+v"(ox));
;       __builtin_amdgcn_global_load_lds((const unsigned*)(wk + ow), (unsigned*)(shm + buf * STAGE_B + wid * 1024 + i * 8192), 16, 0, 0);
;       __builtin_amdgcn_global_load_lds((const unsigned*)(xk + ox), (unsigned*)(shm + buf * STAGE_B + TILE_B + wid * 1024 + i * 8192), 16, 0, 0);
;     }
;     ...
;       for (int ks = 0; ks < 2; ++ks) {
;         const int kx = (wid >> 2) ? (1 - 2 * ks) * 1024 : 0;
;         bf16x8 At[8], Bf[4];
; #pragma unroll
;         for (int m = 0; m < 8; ++m) At[m] = *(const bf16x8*)(SAp + (2 * m + ks) * 1024 + kx);
; #pragma unroll
;         for (int n = 0; n < 4; ++n) Bf[n] = *(const bf16x8*)(SBp + (2 * n + ks) * 1024 + kx);
; #pragma unroll
;         for (int m = 0; m < 8; ++m)
; #pragma unroll
;           for (int n = 0; n < 4; ++n) acc[m][n] = mfma16(At[m], Bf[n], acc[m][n]);
;         __builtin_amdgcn_sched_barrier(0);
;         if (ks == 0 && wid >= 4) {
;           if (st_own) stage(cur ^ 1, n0, m0, kt0 + t + 1);
;           else if (st_next) stage(cur ^ 1, n1, m1, kt1);
;         }
.Lmy_xf_1760:
	s_add_u32 s98, s12, s49
	s_addc_u32 s99, s13, 0
	s_add_u32 s98, s98, 0x80
	s_addc_u32 s99, s99, 0
	s_add_u32 s100, s47, s49
	s_addc_u32 s101, s48, 0
	s_add_u32 s100, s100, 0x80
	s_addc_u32 s101, s101, 0
	s_xor_b32 m0, s51, 0x10000
	s_add_i32 m0, m0, s14
	s_waitcnt lgkmcnt(2)
	v_mfma_f32_16x16x32_bf16 v[124:127], v[220:223], v[134:137], v[124:127]
	v_mfma_f32_16x16x32_bf16 v[120:123], v[220:223], v[142:145], v[120:123]
	v_mfma_f32_16x16x32_bf16 v[116:119], v[220:223], v[146:149], v[116:119]
	v_mfma_f32_16x16x32_bf16 v[112:115], v[220:223], v[150:153], v[112:115]
	global_load_lds_dwordx4 v194, s[98:99]
	ds_read_b128 v[236:239], v154 offset:8192
	s_add_i32 m0, m0, 0x8000
	s_waitcnt lgkmcnt(3)
	v_mfma_f32_16x16x32_bf16 v[108:111], v[224:227], v[134:137], v[108:111]
	v_mfma_f32_16x16x32_bf16 v[104:107], v[224:227], v[142:145], v[104:107]
	v_mfma_f32_16x16x32_bf16 v[100:103], v[224:227], v[146:149], v[100:103]
	v_mfma_f32_16x16x32_bf16 v[96:99], v[224:227], v[150:153], v[96:99]
	global_load_lds_dwordx4 v194, s[100:101]
	ds_read_b128 v[240:243], v154 offset:10240
	s_add_i32 m0, m0, 0xffffa000
	s_waitcnt lgkmcnt(3)
	v_mfma_f32_16x16x32_bf16 v[92:95], v[228:231], v[134:137], v[92:95]
	v_mfma_f32_16x16x32_bf16 v[88:91], v[228:231], v[142:145], v[88:91]
	v_mfma_f32_16x16x32_bf16 v[84:87], v[228:231], v[146:149], v[84:87]
	v_mfma_f32_16x16x32_bf16 v[80:83], v[228:231], v[150:153], v[80:83]
	global_load_lds_dwordx4 v195, s[98:99]
	ds_read_b128 v[244:247], v154 offset:12288
	s_add_i32 m0, m0, 0x8000
	s_waitcnt lgkmcnt(3)
	v_mfma_f32_16x16x32_bf16 v[76:79], v[232:235], v[134:137], v[76:79]
	v_mfma_f32_16x16x32_bf16 v[72:75], v[232:235], v[142:145], v[72:75]
	v_mfma_f32_16x16x32_bf16 v[68:71], v[232:235], v[146:149], v[68:71]
	v_mfma_f32_16x16x32_bf16 v[64:67], v[232:235], v[150:153], v[64:67]
	global_load_lds_dwordx4 v195, s[100:101]
	ds_read_b128 v[248:251], v154 offset:14336
	s_add_i32 m0, m0, 0xffffa000
	s_waitcnt lgkmcnt(3)
	v_mfma_f32_16x16x32_bf16 v[60:63], v[236:239], v[134:137], v[60:63]
	v_mfma_f32_16x16x32_bf16 v[56:59], v[236:239], v[142:145], v[56:59]
	v_mfma_f32_16x16x32_bf16 v[52:55], v[236:239], v[146:149], v[52:55]
	v_mfma_f32_16x16x32_bf16 v[48:51], v[236:239], v[150:153], v[48:51]
	global_load_lds_dwordx4 v196, s[98:99]
	s_add_i32 m0, m0, 0x8000
	s_waitcnt lgkmcnt(2)
	v_mfma_f32_16x16x32_bf16 v[44:47], v[240:243], v[134:137], v[44:47]
	v_mfma_f32_16x16x32_bf16 v[40:43], v[240:243], v[142:145], v[40:43]
	v_mfma_f32_16x16x32_bf16 v[36:39], v[240:243], v[146:149], v[36:39]
	v_mfma_f32_16x16x32_bf16 v[32:35], v[240:243], v[150:153], v[32:35]
	global_load_lds_dwordx4 v196, s[100:101]
	s_add_i32 m0, m0, 0xffffa000
	s_waitcnt lgkmcnt(1)
	v_mfma_f32_16x16x32_bf16 v[28:31], v[244:247], v[134:137], v[28:31]
	v_mfma_f32_16x16x32_bf16 v[24:27], v[244:247], v[142:145], v[24:27]
	v_mfma_f32_16x16x32_bf16 v[20:23], v[244:247], v[146:149], v[20:23]
	v_mfma_f32_16x16x32_bf16 v[16:19], v[244:247], v[150:153], v[16:19]
	global_load_lds_dwordx4 v197, s[98:99]
	s_add_i32 m0, m0, 0x8000
	s_waitcnt lgkmcnt(0)
	v_mfma_f32_16x16x32_bf16 v[12:15], v[248:251], v[134:137], v[12:15]
	v_mfma_f32_16x16x32_bf16 v[8:11], v[248:251], v[142:145], v[8:11]
	v_mfma_f32_16x16x32_bf16 v[4:7], v[248:251], v[146:149], v[4:7]
	v_mfma_f32_16x16x32_bf16 v[0:3], v[248:251], v[150:153], v[0:3]
	global_load_lds_dwordx4 v197, s[100:101]
	s_and_b64 vcc, exec, s[0:1]
	s_branch .LBB0_1759
	s_xor_b32 s10, s51, 0x10000
	s_add_i32 s16, s14, s10
	s_add_i32 s17, s16, 0xe000
	s_add_i32 s18, s16, 0x6000
	s_add_i32 s19, s16, 0xc000
	s_add_i32 s28, s16, 0x4000
	s_add_i32 s29, s16, 0xa000
	s_add_i32 s33, s16, 0x2000
	s_add_i32 s51, s16, 0x8000
	s_ashr_i32 s53, s49, 31
	s_add_u32 s10, s47, s49
	s_addc_u32 s11, s48, s53
	s_add_u32 s52, s12, s49
	s_addc_u32 s53, s13, s53
	v_mov_b32_e32 v192, v194
	v_mov_b32_e32 v130, v194
	v_mov_b32_e32 v131, v193
	v_lshl_add_u64 v[132:133], s[52:53], 0, v[192:193]
	v_lshl_add_u64 v[132:133], v[132:133], 0, s[6:7]
	s_mov_b32 m0, s16
	v_lshl_add_u64 v[130:131], s[10:11], 0, v[130:131]
	global_load_lds_dwordx4 v[132:133], off
	v_lshl_add_u64 v[130:131], v[130:131], 0, s[6:7]
	s_mov_b32 m0, s51
	v_mov_b32_e32 v192, v195
	global_load_lds_dwordx4 v[130:131], off
	v_mov_b32_e32 v130, v195
	v_mov_b32_e32 v131, v193
	v_lshl_add_u64 v[132:133], s[52:53], 0, v[192:193]
	v_lshl_add_u64 v[132:133], v[132:133], 0, s[6:7]
	s_mov_b32 m0, s33
	v_lshl_add_u64 v[130:131], s[10:11], 0, v[130:131]
	global_load_lds_dwordx4 v[132:133], off
	v_lshl_add_u64 v[130:131], v[130:131], 0, s[6:7]
	s_mov_b32 m0, s29
	v_mov_b32_e32 v192, v196
	global_load_lds_dwordx4 v[130:131], off
	v_mov_b32_e32 v130, v196
	v_mov_b32_e32 v131, v193
	v_lshl_add_u64 v[132:133], s[52:53], 0, v[192:193]
	v_lshl_add_u64 v[132:133], v[132:133], 0, s[6:7]
	s_mov_b32 m0, s28
	v_lshl_add_u64 v[130:131], s[10:11], 0, v[130:131]
	global_load_lds_dwordx4 v[132:133], off
	v_lshl_add_u64 v[130:131], v[130:131], 0, s[6:7]
	s_mov_b32 m0, s19
	v_mov_b32_e32 v192, v197
	global_load_lds_dwordx4 v[130:131], off
	v_mov_b32_e32 v130, v197
	v_mov_b32_e32 v131, v193
	v_lshl_add_u64 v[132:133], s[52:53], 0, v[192:193]
	v_lshl_add_u64 v[132:133], v[132:133], 0, s[6:7]
	s_mov_b32 m0, s18
	v_lshl_add_u64 v[130:131], s[10:11], 0, v[130:131]
	global_load_lds_dwordx4 v[132:133], off
	v_lshl_add_u64 v[130:131], v[130:131], 0, s[6:7]
	s_mov_b32 m0, s17
	s_nop 0
	global_load_lds_dwordx4 v[130:131], off
	s_branch .LBB0_1759

; DEVI f32x4 mfma16(bf16x8 a, bf16x8 b, f32x4 c) { return __builtin_amdgcn_mfma_f32_16x16x32_bf16(a, b, c, 0, 0, 0); }
; template <int MODE, class Epi>
; DEVI void gemm256_phase(int sw, const bf16_t* __restrict__ W, int ldw, const bf16_t* __restrict__ X, int ldx, int K, int nN, char* shm, const Epi& epi) {
;     ...
;     for (int t = 0; t < ntk; ++t) {
;       const int cur = (b0 + t) & 1;
;       const bool st_own = t + 1 < ntk, st_next = !st_own && has_next;
;       if (wid < 4) {
;         if (st_own) stage(cur ^ 1, n0, m0, kt0 + t + 1);
;         else if (st_next) stage(cur ^ 1, n1, m1, kt1);
;       }
;       const char* SAp = shm + cur * STAGE_B + wr * (16 * 1024) + lds_lo;
;       const char* SBp = shm + cur * STAGE_B + TILE_B + wc * (8 * 1024) + lds_lo;
; #pragma unroll
;       for (int ks = 0; ks < 2; ++ks) {
;         const int kx = (wid >> 2) ? (1 - 2 * ks) * 1024 : 0;
;         bf16x8 At[8], Bf[4];
; #pragma unroll
;         for (int m = 0; m < 8; ++m) At[m] = *(const bf16x8*)(SAp + (2 * m + ks) * 1024 + kx);
; #pragma unroll
;         for (int n = 0; n < 4; ++n) Bf[n] = *(const bf16x8*)(SBp + (2 * n + ks) * 1024 + kx);
; #pragma unroll
;         for (int m = 0; m < 8; ++m)
; #pragma unroll
;           for (int n = 0; n < 4; ++n) acc[m][n] = mfma16(At[m], Bf[n], acc[m][n]);
;         __builtin_amdgcn_sched_barrier(0);
;         if (ks == 0 && wid >= 4) {
;           if (st_own) stage(cur ^ 1, n0, m0, kt0 + t + 1);
;           else if (st_next) stage(cur ^ 1, n1, m1, kt1);
;         }
;       }
;       asm volatile("s_waitcnt vmcnt(0)" ::: "memory");
;       __syncthreads();
;     }
.LBB0_1800:
	v_add_u32_e32 v154, s54, v129
	ds_read_b128 v[220:223], v154 offset:1024
	v_add_u32_e32 v128, s54, v128
	ds_read_b128 v[134:137], v128 offset:33792
	ds_read_b128 v[224:227], v154 offset:3072
	ds_read_b128 v[142:145], v128 offset:35840
	ds_read_b128 v[146:149], v128 offset:37888
	ds_read_b128 v[150:153], v128 offset:39936
	ds_read_b128 v[228:231], v154 offset:5120
	ds_read_b128 v[232:235], v154 offset:7168
	s_waitcnt lgkmcnt(2)
	v_mfma_f32_16x16x32_bf16 v[124:127], v[220:223], v[134:137], v[124:127]
	v_mfma_f32_16x16x32_bf16 v[120:123], v[220:223], v[142:145], v[120:123]
	v_mfma_f32_16x16x32_bf16 v[116:119], v[220:223], v[146:149], v[116:119]
	v_mfma_f32_16x16x32_bf16 v[112:115], v[220:223], v[150:153], v[112:115]
	ds_read_b128 v[236:239], v154 offset:9216
	s_waitcnt lgkmcnt(3)
	v_mfma_f32_16x16x32_bf16 v[108:111], v[224:227], v[134:137], v[108:111]
	v_mfma_f32_16x16x32_bf16 v[104:107], v[224:227], v[142:145], v[104:107]
	v_mfma_f32_16x16x32_bf16 v[100:103], v[224:227], v[146:149], v[100:103]
	v_mfma_f32_16x16x32_bf16 v[96:99], v[224:227], v[150:153], v[96:99]
	ds_read_b128 v[240:243], v154 offset:11264
	s_waitcnt lgkmcnt(3)
	v_mfma_f32_16x16x32_bf16 v[92:95], v[228:231], v[134:137], v[92:95]
	v_mfma_f32_16x16x32_bf16 v[88:91], v[228:231], v[142:145], v[88:91]
	v_mfma_f32_16x16x32_bf16 v[84:87], v[228:231], v[146:149], v[84:87]
	v_mfma_f32_16x16x32_bf16 v[80:83], v[228:231], v[150:153], v[80:83]
	ds_read_b128 v[244:247], v154 offset:13312
	s_waitcnt lgkmcnt(3)
	v_mfma_f32_16x16x32_bf16 v[76:79], v[232:235], v[134:137], v[76:79]
	v_mfma_f32_16x16x32_bf16 v[72:75], v[232:235], v[142:145], v[72:75]
	v_mfma_f32_16x16x32_bf16 v[68:71], v[232:235], v[146:149], v[68:71]
	v_mfma_f32_16x16x32_bf16 v[64:67], v[232:235], v[150:153], v[64:67]
	ds_read_b128 v[248:251], v154 offset:15360
	s_waitcnt lgkmcnt(3)
	v_mfma_f32_16x16x32_bf16 v[60:63], v[236:239], v[134:137], v[60:63]
	v_mfma_f32_16x16x32_bf16 v[56:59], v[236:239], v[142:145], v[56:59]
	v_mfma_f32_16x16x32_bf16 v[52:55], v[236:239], v[146:149], v[52:55]
	v_mfma_f32_16x16x32_bf16 v[48:51], v[236:239], v[150:153], v[48:51]
	s_waitcnt lgkmcnt(2)
	v_mfma_f32_16x16x32_bf16 v[44:47], v[240:243], v[134:137], v[44:47]
	v_mfma_f32_16x16x32_bf16 v[40:43], v[240:243], v[142:145], v[40:43]
	v_mfma_f32_16x16x32_bf16 v[36:39], v[240:243], v[146:149], v[36:39]
	v_mfma_f32_16x16x32_bf16 v[32:35], v[240:243], v[150:153], v[32:35]
	s_addk_i32 s69, 0x80
	s_cmp_eq_u32 s68, s70
	s_cbranch_scc1 .Lmy_xexit_1801
	s_add_i32 s2, s52, s70
	s_and_b32 s71, s2, 1
	s_add_i32 s70, s70, 1
	s_cmp_lt_i32 s70, s58
	s_cselect_b64 s[2:3], -1, 0
	s_cmp_ge_i32 s70, s58
	s_cselect_b64 s[36:37], -1, 0
	v_cndmask_b32_e64 v128, 0, 1, s[2:3]
	s_and_b64 s[36:37], s[28:29], s[36:37]
	s_and_b64 vcc, exec, s[0:1]
	v_cmp_ne_u32_e64 s[2:3], 1, v128
	s_lshl_b32 s38, s71, 16
	s_add_i32 s16, s38, s49
	v_add_u32_e32 v129, s16, v194
	v_add_u32_e32 v253, s53, v129
	s_or_b32 s16, s38, s50
	v_add_u32_e32 v128, s16, v194
	v_add_u32_e32 v252, s53, v128
	s_waitcnt lgkmcnt(0)
	s_waitcnt vmcnt(0)
	s_barrier
	ds_read_b128 v[220:223], v253
	ds_read_b128 v[224:227], v253 offset:2048
	v_mfma_f32_16x16x32_bf16 v[28:31], v[244:247], v[134:137], v[28:31]
	v_mfma_f32_16x16x32_bf16 v[12:15], v[248:251], v[134:137], v[12:15]
	ds_read_b128 v[134:137], v252 offset:32768
	v_mfma_f32_16x16x32_bf16 v[24:27], v[244:247], v[142:145], v[24:27]
	v_mfma_f32_16x16x32_bf16 v[8:11], v[248:251], v[142:145], v[8:11]
	ds_read_b128 v[142:145], v252 offset:34816
	v_mfma_f32_16x16x32_bf16 v[20:23], v[244:247], v[146:149], v[20:23]
	v_mfma_f32_16x16x32_bf16 v[4:7], v[248:251], v[146:149], v[4:7]
	ds_read_b128 v[146:149], v252 offset:36864
	v_mfma_f32_16x16x32_bf16 v[16:19], v[244:247], v[150:153], v[16:19]
	v_mfma_f32_16x16x32_bf16 v[0:3], v[248:251], v[150:153], v[0:3]
	ds_read_b128 v[150:153], v252 offset:38912
	ds_read_b128 v[228:231], v253 offset:4096
	ds_read_b128 v[232:235], v253 offset:6144
	v_mov_b32_e32 v154, v253
	s_branch .Lmy_xf_1801

; DEVI f32x4 mfma16(bf16x8 a, bf16x8 b, f32x4 c) { return __builtin_amdgcn_mfma_f32_16x16x32_bf16(a, b, c, 0, 0, 0); }
; template <int MODE, class Epi>
; DEVI void gemm256_phase(int sw, const bf16_t* __restrict__ W, int ldw, const bf16_t* __restrict__ X, int ldx, int K, int nN, char* shm, const Epi& epi) {
;     ...
;   auto stage = [&](int buf, int n0, int m0, int kt) {
;     const char* wk = (const char*)(W + (size_t)n0 * ldw) + kt * 128;
;     const char* xk = (const char*)(X + (size_t)m0 * ldx) + kt * 128;
; #pragma unroll
;     for (int i = 0; i < 4; ++i) {
;       unsigned ow = offW[i], ox = offX[i];
;       asm volatile("" : "+v"(ow), "+v"(ox));
;       __builtin_amdgcn_global_load_lds((const unsigned*)(wk + ow), (unsigned*)(shm + buf * STAGE_B + wid * 1024 + i * 8192), 16, 0, 0);
;       __builtin_amdgcn_global_load_lds((const unsigned*)(xk + ox), (unsigned*)(shm + buf * STAGE_B + TILE_B + wid * 1024 + i * 8192), 16, 0, 0);
;     }
;     ...
;       for (int ks = 0; ks < 2; ++ks) {
;         const int kx = (wid >> 2) ? (1 - 2 * ks) * 1024 : 0;
;         bf16x8 At[8], Bf[4];
; #pragma unroll
;         for (int m = 0; m < 8; ++m) At[m] = *(const bf16x8*)(SAp + (2 * m + ks) * 1024 + kx);
; #pragma unroll
;         for (int n = 0; n < 4; ++n) Bf[n] = *(const bf16x8*)(SBp + (2 * n + ks) * 1024 + kx);
; #pragma unroll
;         for (int m = 0; m < 8; ++m)
; #pragma unroll
;           for (int n = 0; n < 4; ++n) acc[m][n] = mfma16(At[m], Bf[n], acc[m][n]);
;         __builtin_amdgcn_sched_barrier(0);
;         if (ks == 0 && wid >= 4) {
;           if (st_own) stage(cur ^ 1, n0, m0, kt0 + t + 1);
;           else if (st_next) stage(cur ^ 1, n1, m1, kt1);
;         }
.Lmy_xf_1801:
	s_add_u32 s98, s64, s69
	s_addc_u32 s99, s65, 0
	s_add_u32 s98, s98, 0x80
	s_addc_u32 s99, s99, 0
	s_add_u32 s100, s66, s69
	s_addc_u32 s101, s67, 0
	s_add_u32 s100, s100, 0x80
	s_addc_u32 s101, s101, 0
	s_xor_b32 m0, s38, 0x10000
	s_add_i32 m0, m0, s48
	s_waitcnt lgkmcnt(2)
	v_mfma_f32_16x16x32_bf16 v[124:127], v[220:223], v[134:137], v[124:127]
	v_mfma_f32_16x16x32_bf16 v[120:123], v[220:223], v[142:145], v[120:123]
	v_mfma_f32_16x16x32_bf16 v[116:119], v[220:223], v[146:149], v[116:119]
	v_mfma_f32_16x16x32_bf16 v[112:115], v[220:223], v[150:153], v[112:115]
	global_load_lds_dwordx4 v190, s[98:99]
	ds_read_b128 v[236:239], v154 offset:8192
	s_add_i32 m0, m0, 0x8000
	s_waitcnt lgkmcnt(3)
	v_mfma_f32_16x16x32_bf16 v[108:111], v[224:227], v[134:137], v[108:111]
	v_mfma_f32_16x16x32_bf16 v[104:107], v[224:227], v[142:145], v[104:107]
	v_mfma_f32_16x16x32_bf16 v[100:103], v[224:227], v[146:149], v[100:103]
	v_mfma_f32_16x16x32_bf16 v[96:99], v[224:227], v[150:153], v[96:99]
	global_load_lds_dwordx4 v190, s[100:101]
	ds_read_b128 v[240:243], v154 offset:10240
	s_add_i32 m0, m0, 0xffffa000
	s_waitcnt lgkmcnt(3)
	v_mfma_f32_16x16x32_bf16 v[92:95], v[228:231], v[134:137], v[92:95]
	v_mfma_f32_16x16x32_bf16 v[88:91], v[228:231], v[142:145], v[88:91]
	v_mfma_f32_16x16x32_bf16 v[84:87], v[228:231], v[146:149], v[84:87]
	v_mfma_f32_16x16x32_bf16 v[80:83], v[228:231], v[150:153], v[80:83]
	global_load_lds_dwordx4 v191, s[98:99]
	ds_read_b128 v[244:247], v154 offset:12288
	s_add_i32 m0, m0, 0x8000
	s_waitcnt lgkmcnt(3)
	v_mfma_f32_16x16x32_bf16 v[76:79], v[232:235], v[134:137], v[76:79]
	v_mfma_f32_16x16x32_bf16 v[72:75], v[232:235], v[142:145], v[72:75]
	v_mfma_f32_16x16x32_bf16 v[68:71], v[232:235], v[146:149], v[68:71]
	v_mfma_f32_16x16x32_bf16 v[64:67], v[232:235], v[150:153], v[64:67]
	global_load_lds_dwordx4 v191, s[100:101]
	ds_read_b128 v[248:251], v154 offset:14336
	s_add_i32 m0, m0, 0xffffa000
	s_waitcnt lgkmcnt(3)
	v_mfma_f32_16x16x32_bf16 v[60:63], v[236:239], v[134:137], v[60:63]
	v_mfma_f32_16x16x32_bf16 v[56:59], v[236:239], v[142:145], v[56:59]
	v_mfma_f32_16x16x32_bf16 v[52:55], v[236:239], v[146:149], v[52:55]
	v_mfma_f32_16x16x32_bf16 v[48:51], v[236:239], v[150:153], v[48:51]
	global_load_lds_dwordx4 v192, s[98:99]
	s_add_i32 m0, m0, 0x8000
	s_waitcnt lgkmcnt(2)
	v_mfma_f32_16x16x32_bf16 v[44:47], v[240:243], v[134:137], v[44:47]
	v_mfma_f32_16x16x32_bf16 v[40:43], v[240:243], v[142:145], v[40:43]
	v_mfma_f32_16x16x32_bf16 v[36:39], v[240:243], v[146:149], v[36:39]
	v_mfma_f32_16x16x32_bf16 v[32:35], v[240:243], v[150:153], v[32:35]
	global_load_lds_dwordx4 v192, s[100:101]
	s_add_i32 m0, m0, 0xffffa000
	s_waitcnt lgkmcnt(1)
	v_mfma_f32_16x16x32_bf16 v[28:31], v[244:247], v[134:137], v[28:31]
	v_mfma_f32_16x16x32_bf16 v[24:27], v[244:247], v[142:145], v[24:27]
	v_mfma_f32_16x16x32_bf16 v[20:23], v[244:247], v[146:149], v[20:23]
	v_mfma_f32_16x16x32_bf16 v[16:19], v[244:247], v[150:153], v[16:19]
	global_load_lds_dwordx4 v193, s[98:99]
	s_add_i32 m0, m0, 0x8000
	s_waitcnt lgkmcnt(0)
	v_mfma_f32_16x16x32_bf16 v[12:15], v[248:251], v[134:137], v[12:15]
	v_mfma_f32_16x16x32_bf16 v[8:11], v[248:251], v[142:145], v[8:11]
	v_mfma_f32_16x16x32_bf16 v[4:7], v[248:251], v[146:149], v[4:7]
	v_mfma_f32_16x16x32_bf16 v[0:3], v[248:251], v[150:153], v[0:3]
	global_load_lds_dwordx4 v193, s[100:101]
	s_andn2_b64 vcc, exec, s[8:9]
	s_branch .LBB0_1800
	s_and_b64 vcc, exec, s[2:3]
	s_xor_b32 s44, s38, 0x10000
	s_cbranch_vccnz .LBB0_1813
	s_ashr_i32 s16, s69, 31
	s_add_u32 s40, s64, s69
	s_addc_u32 s41, s65, s16
	s_add_u32 s2, s40, 0x80
	s_addc_u32 s3, s41, 0
	s_add_u32 s42, s66, s69
	s_addc_u32 s43, s67, s16
	s_add_u32 s38, s42, 0x80
	v_mov_b32_e32 v188, v190
	v_mov_b32_e32 v130, v190
	s_addc_u32 s39, s43, 0
	s_add_i32 s16, s48, s44
	v_lshl_add_u64 v[132:133], s[40:41], 0, v[188:189]
	v_mov_b32_e32 v131, v189
	v_lshl_add_u64 v[132:133], v[132:133], 0, s[12:13]
	s_mov_b32 m0, s16
	v_lshl_add_u64 v[130:131], s[42:43], 0, v[130:131]
	global_load_lds_dwordx4 v[132:133], off
	v_lshl_add_u64 v[130:131], v[130:131], 0, s[12:13]
	s_add_i32 m0, s16, 0x8000
	v_mov_b32_e32 v188, v191
	global_load_lds_dwordx4 v[130:131], off
	v_mov_b32_e32 v130, v191
	v_mov_b32_e32 v131, v189
	v_lshl_add_u64 v[132:133], s[40:41], 0, v[188:189]
	v_lshl_add_u64 v[132:133], v[132:133], 0, s[12:13]
	s_add_i32 m0, s16, 0x2000
	v_lshl_add_u64 v[130:131], s[42:43], 0, v[130:131]
	global_load_lds_dwordx4 v[132:133], off
	v_lshl_add_u64 v[130:131], v[130:131], 0, s[12:13]
	s_add_i32 m0, s16, 0xa000
	v_mov_b32_e32 v188, v192
	global_load_lds_dwordx4 v[130:131], off
	v_mov_b32_e32 v130, v192
	v_mov_b32_e32 v131, v189
	v_lshl_add_u64 v[132:133], s[40:41], 0, v[188:189]
	v_lshl_add_u64 v[132:133], v[132:133], 0, s[12:13]
	s_add_i32 m0, s16, 0x4000
	v_lshl_add_u64 v[130:131], s[42:43], 0, v[130:131]
	global_load_lds_dwordx4 v[132:133], off
	v_lshl_add_u64 v[130:131], v[130:131], 0, s[12:13]
	s_add_i32 m0, s16, 0xc000
	s_nop 0
	global_load_lds_dwordx4 v[130:131], off
	v_mov_b32_e32 v130, v193
	v_mov_b32_e32 v131, v193
	s_mov_b64 s[40:41], -1
	s_cbranch_execz .LBB0_1814
	s_branch .LBB0_1817
